# non-temporal loads for all once-read f32 weight tiles in the conversion passes (PA-trailing transposes, PE-trailing next-layer w_in)
# speedup vs baseline: 1.0728x; 1.0046x over previous
; #define GAS __attribute__((address_space(1)))
; #define LAS __attribute__((address_space(3)))
; template <int GU>
; __device__ __forceinline__ void p0_transpose_item(const float* W, int N, const float* kscale, bf16* WT, int ldt, int koff, LAS float* scr, int item, int lane) {
;     const int nblk = N / 64, kb = item / nblk, nb = item % nblk, k0 = 64 * kb, n0 = 64 * nb;
;     const int q = lane >> 4, cc = lane & 15;
;     f32x4 v[16];
; #pragma unroll
;     for (int i = 0; i < 16; ++i) v[i] = *(const GAS f32x4*)(W + (size_t)(k0 + 4 * i + q) * N + n0 + 4 * cc);
;     const int c = lane & 7;
;     f32x4 s0 = (f32x4){1.f, 1.f, 1.f, 1.f}, s1 = s0;
;     if (kscale) { s0 = *(const GAS f32x4*)(kscale + k0 + 8 * c); s1 = *(const GAS f32x4*)(kscale + k0 + 8 * c + 4); }
; #pragma unroll
;     for (int i = 0; i < 16; ++i) { LAS float* d = scr + (4 * i + q) * TR_PITCH + 4 * cc; d[0] = v[i].x; d[1] = v[i].y; d[2] = v[i].z; d[3] = v[i].w; }
; __device__ __forceinline__ void convert_layer_items(const float* const* in, unsigned char* ws, int l, int first, int stride, LAS float* scr, int lane, int mode) {
;     ...
;     for (int it = first; it < count; it += stride) {
;         int r = mode == 0 ? it + I_P : (mode == 1 ? (it < I_P ? it : it + I_IN) : it);
;         if (r < I_P) { p0_pooleff_item(in[3] + (size_t)l * 4 * 128 * 128, in[4] + (size_t)l * POOLW, in[6] + (size_t)l * POOLW * DM, (bf16*)(wl + WO_PA), r, lane); continue; } r -= I_P;
;         if (r < I_IN) { p0_transpose_item<3>(in[2] + (size_t)l * DM * INW, INW, in[1] + (size_t)l * DM, (bf16*)(wl + WO_IN), DM, 0, scr, r, lane); continue; } r -= I_IN;
;         if (r < I_A) { p0_transpose_item<0>(in[7] + (size_t)l * 512 * DM, DM, nullptr, (bf16*)(wl + WO_PA), DM, 512, scr, r, lane); continue; } r -= I_A;
;         if (r < I_O) { p0_transpose_item<0>(in[8] + (size_t)l * DM * DM, DM, nullptr, (bf16*)(wl + WO_OUT), DM, 0, scr, r, lane); continue; } r -= I_O;
;         if (r < I_G) { p0_transpose_item<1>(in[10] + (size_t)l * DM * DFF, DFF, in[9] + (size_t)l * DM, (bf16*)(wl + WO_GU), DM, 0, scr, r, lane); continue; } r -= I_G;
;         if (r < I_G) { p0_transpose_item<2>(in[11] + (size_t)l * DM * DFF, DFF, in[9] + (size_t)l * DM, (bf16*)(wl + WO_GU), DM, 0, scr, r, lane); continue; } r -= I_G;
;         p0_transpose_item<0>(in[12] + (size_t)l * DFF * DM, DM, nullptr, (bf16*)(wl + WO_D), DFF, 0, scr, r, lane);
.LBB0_174:
	s_add_i32 s23, s48, 0x340
	s_cmpk_lt_i32 s48, 0x400
	s_cselect_b32 s23, s48, s23
	s_cmpk_gt_i32 s23, 0x3ff
	s_mov_b64 s[36:37], -1
	s_cbranch_scc0 .LBB0_221
	s_cmpk_gt_u32 s23, 0x73f
	s_cbranch_scc0 .LBB0_199
	s_cmpk_gt_u32 s23, 0x7bf
	s_cbranch_scc0 .LBB0_196
	s_cmpk_gt_u32 s23, 0x8bf
	s_cbranch_scc0 .LBB0_193
	s_cmpk_gt_u32 s23, 0xb7f
	s_cbranch_scc0 .LBB0_187
	s_cmpk_gt_u32 s23, 0xe3f
	s_cbranch_scc0 .LBB0_181
	s_add_i32 s24, s23, 0xfffff1c0
	s_lshl_b32 s25, s24, 2
	s_lshl_b32 s24, s24, 6
	s_and_b32 s26, s25, 0xfc0
	s_and_b32 s24, s24, 0x3c0
	v_add_u32_e32 v2, s26, v102
	v_add_u32_e32 v4, s26, v103
	s_lshl_b32 s84, s24, 2
	v_ashrrev_i32_e32 v3, 31, v2
	v_ashrrev_i32_e32 v5, 31, v4
	v_lshl_add_u64 v[62:63], v[86:87], 0, s[84:85]
	v_lshlrev_b64 v[2:3], 12, v[2:3]
	v_lshlrev_b64 v[4:5], 12, v[4:5]
	v_lshl_add_u64 v[2:3], v[62:63], 0, v[2:3]
	v_lshl_add_u64 v[6:7], v[62:63], 0, v[4:5]
	v_add_u32_e32 v10, s26, v104
	v_add_u32_e32 v12, s26, v105
	global_load_dwordx4 v[2:5], v[2:3], off nt
	s_nop 0
	global_load_dwordx4 v[6:9], v[6:7], off nt
	v_ashrrev_i32_e32 v11, 31, v10
	v_ashrrev_i32_e32 v13, 31, v12
	v_lshlrev_b64 v[10:11], 12, v[10:11]
	v_lshlrev_b64 v[12:13], 12, v[12:13]
	v_lshl_add_u64 v[10:11], v[62:63], 0, v[10:11]
	v_lshl_add_u64 v[14:15], v[62:63], 0, v[12:13]
	global_load_dwordx4 v[10:13], v[10:11], off nt
	s_nop 0
	global_load_dwordx4 v[14:17], v[14:15], off nt
	v_add_u32_e32 v18, s26, v106
	v_add_u32_e32 v20, s26, v107
	v_ashrrev_i32_e32 v19, 31, v18
	v_ashrrev_i32_e32 v21, 31, v20
	v_lshlrev_b64 v[18:19], 12, v[18:19]
	v_lshlrev_b64 v[20:21], 12, v[20:21]
	v_lshl_add_u64 v[18:19], v[62:63], 0, v[18:19]
	v_lshl_add_u64 v[22:23], v[62:63], 0, v[20:21]
	global_load_dwordx4 v[18:21], v[18:19], off nt
	s_nop 0
	global_load_dwordx4 v[22:25], v[22:23], off nt
	v_add_u32_e32 v26, s26, v108
	v_add_u32_e32 v28, s26, v109
	v_ashrrev_i32_e32 v27, 31, v26
	v_ashrrev_i32_e32 v29, 31, v28
	v_lshlrev_b64 v[26:27], 12, v[26:27]
	v_lshlrev_b64 v[28:29], 12, v[28:29]
	v_lshl_add_u64 v[26:27], v[62:63], 0, v[26:27]
	v_lshl_add_u64 v[30:31], v[62:63], 0, v[28:29]
	global_load_dwordx4 v[26:29], v[26:27], off nt
	s_nop 0
	global_load_dwordx4 v[30:33], v[30:31], off nt
	v_add_u32_e32 v34, s26, v110
	v_add_u32_e32 v36, s26, v111
	v_ashrrev_i32_e32 v35, 31, v34
	v_ashrrev_i32_e32 v37, 31, v36
	v_lshlrev_b64 v[34:35], 12, v[34:35]
	v_lshlrev_b64 v[36:37], 12, v[36:37]
	v_lshl_add_u64 v[34:35], v[62:63], 0, v[34:35]
	v_lshl_add_u64 v[38:39], v[62:63], 0, v[36:37]
	global_load_dwordx4 v[34:37], v[34:35], off nt
	s_nop 0
	global_load_dwordx4 v[38:41], v[38:39], off nt
	v_add_u32_e32 v42, s26, v112
	v_add_u32_e32 v44, s26, v113
	v_ashrrev_i32_e32 v43, 31, v42
	v_ashrrev_i32_e32 v45, 31, v44
	v_lshlrev_b64 v[42:43], 12, v[42:43]
	v_lshlrev_b64 v[44:45], 12, v[44:45]
	v_lshl_add_u64 v[42:43], v[62:63], 0, v[42:43]
	v_lshl_add_u64 v[46:47], v[62:63], 0, v[44:45]
	global_load_dwordx4 v[42:45], v[42:43], off nt
	s_nop 0
	global_load_dwordx4 v[46:49], v[46:47], off nt
	v_add_u32_e32 v50, s26, v114
	v_add_u32_e32 v52, s26, v115
	v_ashrrev_i32_e32 v51, 31, v50
	v_ashrrev_i32_e32 v53, 31, v52
	v_lshlrev_b64 v[50:51], 12, v[50:51]
	v_lshlrev_b64 v[52:53], 12, v[52:53]
	v_lshl_add_u64 v[50:51], v[62:63], 0, v[50:51]
	v_lshl_add_u64 v[54:55], v[62:63], 0, v[52:53]
	v_add_u32_e32 v58, s26, v116
	global_load_dwordx4 v[50:53], v[50:51], off nt
	s_nop 0
	global_load_dwordx4 v[54:57], v[54:55], off nt
	v_ashrrev_i32_e32 v59, 31, v58
	s_or_b32 s25, s25, 60
	v_lshlrev_b64 v[58:59], 12, v[58:59]
	v_add_u32_e32 v64, s25, v102
	v_lshl_add_u64 v[58:59], v[62:63], 0, v[58:59]
	v_ashrrev_i32_e32 v65, 31, v64
	global_load_dwordx4 v[58:61], v[58:59], off nt
	v_lshlrev_b64 v[64:65], 12, v[64:65]
	v_lshl_add_u64 v[62:63], v[62:63], 0, v[64:65]
	global_load_dwordx4 v[62:65], v[62:63], off nt
	s_lshl_b32 s84, s26, 1
	s_movk_i32 s6, 0x1600
	s_mov_b64 s[36:37], 0
	s_waitcnt vmcnt(0)
	ds_write2_b32 v117, v2, v3 offset1:1
	ds_write2_b32 v117, v4, v5 offset0:2 offset1:3
	v_add_u32_e32 v2, 0x410, v117
	ds_write2_b32 v2, v6, v7 offset1:1
	v_add_u32_e32 v2, 0x418, v117
	ds_write2_b32 v2, v8, v9 offset1:1
	v_add_u32_e32 v2, 0x820, v117
	ds_write2_b32 v2, v10, v11 offset1:1
	v_add_u32_e32 v2, 0x828, v117
	ds_write2_b32 v2, v12, v13 offset1:1
	v_add_u32_e32 v2, 0xc30, v117
	ds_write2_b32 v2, v14, v15 offset1:1
	v_add_u32_e32 v2, 0xc38, v117
	ds_write2_b32 v2, v16, v17 offset1:1
	v_add_u32_e32 v2, 0x1040, v117
	ds_write2_b32 v2, v18, v19 offset1:1
	v_add_u32_e32 v2, 0x1048, v117
	ds_write2_b32 v2, v20, v21 offset1:1
	v_add_u32_e32 v2, 0x1450, v117
	ds_write2_b32 v2, v22, v23 offset1:1
	v_add_u32_e32 v2, 0x1458, v117
	ds_write2_b32 v2, v24, v25 offset1:1
	v_add_u32_e32 v2, 0x1860, v117
	v_lshl_add_u64 v[22:23], v[76:77], 0, s[84:85]
	ds_write2_b32 v2, v26, v27 offset1:1
	v_add_u32_e32 v2, 0x1868, v117
	ds_write2_b32 v2, v28, v29 offset1:1
	v_add_u32_e32 v2, 0x1c70, v117
	ds_write2_b32 v2, v30, v31 offset1:1
	v_add_u32_e32 v2, 0x1c78, v117
	ds_write2_b32 v2, v32, v33 offset1:1
	v_add_u32_e32 v2, 0x2080, v117
	v_add_u32_e32 v26, 0x400, v119
	ds_write2_b32 v2, v34, v35 offset1:1
	v_add_u32_e32 v2, 0x2088, v117
	ds_write2_b32 v2, v36, v37 offset1:1
	v_add_u32_e32 v2, 0x2490, v117
	ds_write2_b32 v2, v38, v39 offset1:1
	v_add_u32_e32 v2, 0x2498, v117
	ds_write2_b32 v2, v40, v41 offset1:1
	v_add_u32_e32 v2, 0x28a0, v117
	ds_write2_b32 v2, v42, v43 offset1:1
	v_add_u32_e32 v2, 0x28a8, v117
	ds_write2_b32 v2, v44, v45 offset1:1
	v_add_u32_e32 v2, 0x2cb0, v117
	ds_write2_b32 v2, v46, v47 offset1:1
	v_add_u32_e32 v2, 0x2cb8, v117
	ds_write2_b32 v2, v48, v49 offset1:1
	v_add_u32_e32 v2, 0x30c0, v117
	ds_write2_b32 v2, v50, v51 offset1:1
	v_add_u32_e32 v2, 0x30c8, v117
	ds_write2_b32 v2, v52, v53 offset1:1
	v_add_u32_e32 v2, 0x34d0, v117
	ds_write2_b32 v2, v54, v55 offset1:1
	v_add_u32_e32 v2, 0x34d8, v117
	ds_write2_b32 v2, v56, v57 offset1:1
	v_add_u32_e32 v2, 0x38e0, v117
	ds_write2_b32 v2, v58, v59 offset1:1
	v_add_u32_e32 v2, 0x38e8, v117
	ds_write2_b32 v2, v60, v61 offset1:1
	v_add_u32_e32 v2, 0x3cf0, v117
	ds_write2_b32 v2, v62, v63 offset1:1
	v_add_u32_e32 v2, 0x3cf8, v117
	ds_write2_b32 v2, v64, v65 offset1:1
	s_waitcnt lgkmcnt(0)
; #define GAS __attribute__((address_space(1)))
; #define LAS __attribute__((address_space(3)))
; #define LDS_WAIT() asm volatile("s_waitcnt lgkmcnt(0)" ::: "memory")
; __device__ __forceinline__ unsigned pk2(float lo, float hi) { f32x2p v = {lo, hi}; bf16x2p b = __builtin_convertvector(v, bf16x2p); return __builtin_bit_cast(unsigned, b); }
; template <int GU>
; __device__ __forceinline__ void p0_transpose_item(const float* W, int N, const float* kscale, bf16* WT, int ldt, int koff, LAS float* scr, int item, int lane) {
;     const int nblk = N / 64, kb = item / nblk, nb = item % nblk, k0 = 64 * kb, n0 = 64 * nb;
;     const int q = lane >> 4, cc = lane & 15;
;     f32x4 v[16];
; #pragma unroll
;     for (int i = 0; i < 16; ++i) v[i] = *(const GAS f32x4*)(W + (size_t)(k0 + 4 * i + q) * N + n0 + 4 * cc);
;     const int c = lane & 7;
;     f32x4 s0 = (f32x4){1.f, 1.f, 1.f, 1.f}, s1 = s0;
;     if (kscale) { s0 = *(const GAS f32x4*)(kscale + k0 + 8 * c); s1 = *(const GAS f32x4*)(kscale + k0 + 8 * c + 4); }
; #pragma unroll
;     for (int i = 0; i < 16; ++i) { LAS float* d = scr + (4 * i + q) * TR_PITCH + 4 * cc; d[0] = v[i].x; d[1] = v[i].y; d[2] = v[i].z; d[3] = v[i].w; }
;     LDS_WAIT(); asm volatile("" ::: "memory");
; #pragma unroll
;     for (int j = 0; j < 8; ++j) { const int n = (lane >> 3) + 8 * j; const LAS float* s = scr + (8 * c) * TR_PITCH + n;
;         v4u o; o.x = pk2(s[0 * TR_PITCH] * s0.x, s[1 * TR_PITCH] * s0.y); o.y = pk2(s[2 * TR_PITCH] * s0.z, s[3 * TR_PITCH] * s0.w);
;         o.z = pk2(s[4 * TR_PITCH] * s1.x, s[5 * TR_PITCH] * s1.y); o.w = pk2(s[6 * TR_PITCH] * s1.z, s[7 * TR_PITCH] * s1.w);
;         const int ng = n0 + n; int drow;
;         if (GU == 0) drow = ng;
;         else if (GU == 3) { const int gsel = (ng >= 2304) ? 1 : 0, j = ng - 1280 - 1024 * gsel; drow = (ng < 1280) ? ng : (1280 + 256 * (j >> 7) + 128 * gsel + (j & 127)); }
;         else drow = 256 * (ng >> 7) + (GU - 1) * 128 + (ng & 127);
;         *(GAS v4u*)(WT + (size_t)drow * ldt + koff + k0 + 8 * c) = o; }
	ds_read2_b32 v[6:7], v119 offset0:65 offset1:73
	ds_read2_b32 v[8:9], v119 offset1:8
	ds_read2_b32 v[10:11], v119 offset0:130 offset1:138
	ds_read2_b32 v[12:13], v119 offset0:195 offset1:203
	ds_read2_b32 v[14:15], v26 offset0:4 offset1:12
	ds_read2_b32 v[16:17], v26 offset0:69 offset1:77
	ds_read2_b32 v[18:19], v26 offset0:134 offset1:142
	ds_read2_b32 v[20:21], v26 offset0:199 offset1:207
	s_waitcnt lgkmcnt(6)
	v_cvt_pk_bf16_f32 v2, v8, v6
	v_add_u32_e32 v6, s24, v118
	s_waitcnt lgkmcnt(4)
	v_cvt_pk_bf16_f32 v3, v10, v12
	s_waitcnt lgkmcnt(2)
	v_cvt_pk_bf16_f32 v4, v14, v16
	s_waitcnt lgkmcnt(0)
	v_cvt_pk_bf16_f32 v5, v18, v20
	v_mad_i64_i32 v[24:25], s[26:27], v6, s6, v[22:23]
	global_store_dwordx4 v[24:25], v[2:5], off sc1
	v_add_u32_e32 v6, s24, v120
	s_nop 0
	v_cvt_pk_bf16_f32 v2, v9, v7
	v_cvt_pk_bf16_f32 v3, v11, v13
	v_cvt_pk_bf16_f32 v4, v15, v17
	v_cvt_pk_bf16_f32 v5, v19, v21
	ds_read2_b32 v[8:9], v119 offset0:81 offset1:89
	ds_read2_b32 v[10:11], v119 offset0:16 offset1:24
	ds_read2_b32 v[12:13], v119 offset0:146 offset1:154
	ds_read2_b32 v[14:15], v119 offset0:211 offset1:219
	ds_read2_b32 v[16:17], v26 offset0:20 offset1:28
	ds_read2_b32 v[18:19], v26 offset0:85 offset1:93
	ds_read2_b32 v[20:21], v26 offset0:150 offset1:158
	ds_read2_b32 v[24:25], v26 offset0:215 offset1:223
	v_mad_i64_i32 v[6:7], s[26:27], v6, s6, v[22:23]
	global_store_dwordx4 v[6:7], v[2:5], off sc1
	v_add_u32_e32 v6, s24, v121
	v_mad_i64_i32 v[6:7], s[26:27], v6, s6, v[22:23]
	s_waitcnt lgkmcnt(6)
	v_cvt_pk_bf16_f32 v2, v10, v8
	s_waitcnt lgkmcnt(4)
	v_cvt_pk_bf16_f32 v3, v12, v14
	s_waitcnt lgkmcnt(2)
	v_cvt_pk_bf16_f32 v4, v16, v18
	s_waitcnt lgkmcnt(0)
	v_cvt_pk_bf16_f32 v5, v20, v24
	global_store_dwordx4 v[6:7], v[2:5], off sc1
	v_add_u32_e32 v6, s24, v122
	v_mad_i64_i32 v[6:7], s[26:27], v6, s6, v[22:23]
	v_cvt_pk_bf16_f32 v2, v11, v9
	v_cvt_pk_bf16_f32 v3, v13, v15
	v_cvt_pk_bf16_f32 v4, v17, v19
	v_cvt_pk_bf16_f32 v5, v21, v25
	ds_read2_b32 v[8:9], v119 offset0:32 offset1:40
	ds_read2_b32 v[10:11], v119 offset0:97 offset1:105
	ds_read2_b32 v[12:13], v119 offset0:162 offset1:170
	ds_read2_b32 v[14:15], v119 offset0:227 offset1:235
	ds_read2_b32 v[16:17], v26 offset0:36 offset1:44
	ds_read2_b32 v[18:19], v26 offset0:101 offset1:109
	ds_read2_b32 v[20:21], v26 offset0:166 offset1:174
	ds_read2_b32 v[24:25], v26 offset0:231 offset1:239
	global_store_dwordx4 v[6:7], v[2:5], off sc1
	v_add_u32_e32 v6, s24, v123
	v_mad_i64_i32 v[6:7], s[26:27], v6, s6, v[22:23]
	s_waitcnt lgkmcnt(6)
	v_cvt_pk_bf16_f32 v2, v8, v10
	s_waitcnt lgkmcnt(4)
	v_cvt_pk_bf16_f32 v3, v12, v14
	s_waitcnt lgkmcnt(2)
	v_cvt_pk_bf16_f32 v4, v16, v18
	s_waitcnt lgkmcnt(0)
	v_cvt_pk_bf16_f32 v5, v20, v24
	global_store_dwordx4 v[6:7], v[2:5], off sc1
	v_add_u32_e32 v6, s24, v124
	v_mad_i64_i32 v[6:7], s[26:27], v6, s6, v[22:23]
	v_cvt_pk_bf16_f32 v2, v9, v11
	v_cvt_pk_bf16_f32 v3, v13, v15
	v_cvt_pk_bf16_f32 v4, v17, v19
	v_cvt_pk_bf16_f32 v5, v21, v25
	ds_read2_b32 v[8:9], v119 offset0:48 offset1:56
	ds_read2_b32 v[10:11], v119 offset0:113 offset1:121
	ds_read2_b32 v[12:13], v119 offset0:178 offset1:186
	ds_read2_b32 v[14:15], v119 offset0:243 offset1:251
	ds_read2_b32 v[16:17], v26 offset0:52 offset1:60
	ds_read2_b32 v[18:19], v26 offset0:117 offset1:125
	ds_read2_b32 v[20:21], v26 offset0:182 offset1:190
	ds_read2_b32 v[24:25], v26 offset0:247 offset1:255
	global_store_dwordx4 v[6:7], v[2:5], off sc1
	v_add_u32_e32 v6, s24, v125
	v_mad_i64_i32 v[6:7], s[26:27], v6, s6, v[22:23]
	s_waitcnt lgkmcnt(6)
	v_cvt_pk_bf16_f32 v2, v8, v10
	s_waitcnt lgkmcnt(4)
	v_cvt_pk_bf16_f32 v3, v12, v14
	s_waitcnt lgkmcnt(2)
	v_cvt_pk_bf16_f32 v4, v16, v18
	s_waitcnt lgkmcnt(0)
	v_cvt_pk_bf16_f32 v5, v20, v24
	global_store_dwordx4 v[6:7], v[2:5], off sc1
	v_add_u32_e32 v6, s24, v126
	v_mad_i64_i32 v[6:7], s[24:25], v6, s6, v[22:23]
	v_cvt_pk_bf16_f32 v2, v9, v11
	v_cvt_pk_bf16_f32 v3, v13, v15
	v_cvt_pk_bf16_f32 v4, v17, v19
	v_cvt_pk_bf16_f32 v5, v21, v25
	global_store_dwordx4 v[6:7], v[2:5], off sc1
	s_waitcnt lgkmcnt(0)
.LBB0_181:
	s_andn2_b64 vcc, exec, s[36:37]
	s_cbranch_vccnz .LBB0_186
	s_add_i32 s24, s23, 0xf480
	s_and_b32 s25, s24, 0xffff
	s_mul_i32 s25, s25, 0xba2f
	s_lshr_b32 s26, s25, 21
	s_mul_i32 s26, s26, 44
	s_sub_i32 s24, s24, s26
	s_lshr_b32 s25, s25, 15
	s_lshl_b32 s26, s24, 8
	s_and_b32 s25, s25, 0xffc0
	s_and_b32 s84, s26, 0x3ff00
	v_add_u32_e32 v8, s25, v102
	v_lshl_add_u64 v[2:3], v[88:89], 0, s[84:85]
	s_movk_i32 s6, 0x2c00
	v_mad_i64_i32 v[4:5], s[26:27], v8, s6, v[2:3]
	v_add_u32_e32 v6, 4, v8
	v_mad_i64_i32 v[6:7], s[26:27], v6, s6, v[2:3]
	global_load_dwordx4 v[72:75], v[4:5], off nt
	global_load_dwordx4 v[54:57], v[6:7], off nt
	v_add_u32_e32 v4, 8, v8
	v_mad_i64_i32 v[4:5], s[26:27], v4, s6, v[2:3]
	v_add_u32_e32 v6, 12, v8
	v_mad_i64_i32 v[6:7], s[26:27], v6, s6, v[2:3]
	global_load_dwordx4 v[68:71], v[4:5], off nt
	global_load_dwordx4 v[46:49], v[6:7], off nt
	v_add_u32_e32 v4, 16, v8
	v_mad_i64_i32 v[4:5], s[26:27], v4, s6, v[2:3]
	v_add_u32_e32 v6, 20, v8
	v_mad_i64_i32 v[6:7], s[26:27], v6, s6, v[2:3]
	global_load_dwordx4 v[62:65], v[4:5], off nt
	global_load_dwordx4 v[38:41], v[6:7], off nt
	v_add_u32_e32 v4, 24, v8
	v_mad_i64_i32 v[4:5], s[26:27], v4, s6, v[2:3]
	v_add_u32_e32 v6, 28, v8
	v_mad_i64_i32 v[6:7], s[26:27], v6, s6, v[2:3]
	global_load_dwordx4 v[58:61], v[4:5], off nt
	global_load_dwordx4 v[26:29], v[6:7], off nt
	v_add_u32_e32 v4, 32, v8
	v_mad_i64_i32 v[4:5], s[26:27], v4, s6, v[2:3]
	v_add_u32_e32 v6, 36, v8
	v_mad_i64_i32 v[6:7], s[26:27], v6, s6, v[2:3]
	global_load_dwordx4 v[50:53], v[4:5], off nt
	global_load_dwordx4 v[22:25], v[6:7], off nt
	v_add_u32_e32 v4, 40, v8
	v_mad_i64_i32 v[4:5], s[26:27], v4, s6, v[2:3]
	v_add_u32_e32 v6, 44, v8
	v_mad_i64_i32 v[6:7], s[26:27], v6, s6, v[2:3]
	global_load_dwordx4 v[42:45], v[4:5], off nt
	global_load_dwordx4 v[18:21], v[6:7], off nt
	v_add_u32_e32 v4, 48, v8
	v_mad_i64_i32 v[4:5], s[26:27], v4, s6, v[2:3]
	v_add_u32_e32 v6, 52, v8
	v_mad_i64_i32 v[6:7], s[26:27], v6, s6, v[2:3]
	global_load_dwordx4 v[30:33], v[4:5], off nt
	global_load_dwordx4 v[10:13], v[6:7], off nt
	v_add_u32_e32 v4, 56, v8
	v_mad_i64_i32 v[4:5], s[26:27], v4, s6, v[2:3]
	v_add_u32_e32 v6, 60, v8
	v_mad_i64_i32 v[2:3], s[26:27], v6, s6, v[2:3]
	global_load_dwordx4 v[34:37], v[4:5], off nt
	global_load_dwordx4 v[14:17], v[2:3], off nt
	v_readlane_b32 s6, v242, 58
	v_readlane_b32 s7, v242, 59
	s_andn2_b64 vcc, exec, s[6:7]
	s_lshl_b32 s24, s24, 6
	s_cbranch_vccnz .LBB0_184
	s_lshl_b32 s84, s25, 2
	v_lshl_add_u64 v[6:7], v[90:91], 0, s[84:85]
	global_load_dwordx4 v[2:5], v[6:7], off offset:16 nt
	s_nop 0
	global_load_dwordx4 v[6:9], v[6:7], off nt
	s_branch .LBB0_185

; #define GAS __attribute__((address_space(1)))
; #define LAS __attribute__((address_space(3)))
; template <int GU>
; __device__ __forceinline__ void p0_transpose_item(const float* W, int N, const float* kscale, bf16* WT, int ldt, int koff, LAS float* scr, int item, int lane) {
;     const int nblk = N / 64, kb = item / nblk, nb = item % nblk, k0 = 64 * kb, n0 = 64 * nb;
;     const int q = lane >> 4, cc = lane & 15;
;     f32x4 v[16];
; #pragma unroll
;     for (int i = 0; i < 16; ++i) v[i] = *(const GAS f32x4*)(W + (size_t)(k0 + 4 * i + q) * N + n0 + 4 * cc);
;     const int c = lane & 7;
;     f32x4 s0 = (f32x4){1.f, 1.f, 1.f, 1.f}, s1 = s0;
;     if (kscale) { s0 = *(const GAS f32x4*)(kscale + k0 + 8 * c); s1 = *(const GAS f32x4*)(kscale + k0 + 8 * c + 4); }
; __device__ __forceinline__ void convert_layer_items(const float* const* in, unsigned char* ws, int l, int first, int stride, LAS float* scr, int lane, int mode) {
;     ...
;         if (r < I_G) { p0_transpose_item<1>(in[10] + (size_t)l * DM * DFF, DFF, in[9] + (size_t)l * DM, (bf16*)(wl + WO_GU), DM, 0, scr, r, lane); continue; } r -= I_G;
.LBB0_187:
	s_andn2_b64 vcc, exec, s[36:37]
	s_cbranch_vccnz .LBB0_192
	s_add_i32 s24, s23, 0xf740
	s_and_b32 s25, s24, 0xffff
	s_mul_i32 s25, s25, 0xba2f
	s_lshr_b32 s26, s25, 21
	s_mul_i32 s26, s26, 44
	s_sub_i32 s24, s24, s26
	s_lshr_b32 s25, s25, 15
	s_lshl_b32 s26, s24, 8
	s_and_b32 s25, s25, 0xffc0
	s_and_b32 s84, s26, 0x3ff00
	v_add_u32_e32 v8, s25, v102
	v_lshl_add_u64 v[2:3], v[92:93], 0, s[84:85]
	s_movk_i32 s6, 0x2c00
	v_mad_i64_i32 v[4:5], s[26:27], v8, s6, v[2:3]
	v_add_u32_e32 v6, 4, v8
	v_mad_i64_i32 v[6:7], s[26:27], v6, s6, v[2:3]
	global_load_dwordx4 v[72:75], v[4:5], off nt
	global_load_dwordx4 v[54:57], v[6:7], off nt
	v_add_u32_e32 v4, 8, v8
	v_mad_i64_i32 v[4:5], s[26:27], v4, s6, v[2:3]
	v_add_u32_e32 v6, 12, v8
	v_mad_i64_i32 v[6:7], s[26:27], v6, s6, v[2:3]
	global_load_dwordx4 v[68:71], v[4:5], off nt
	global_load_dwordx4 v[46:49], v[6:7], off nt
	v_add_u32_e32 v4, 16, v8
	v_mad_i64_i32 v[4:5], s[26:27], v4, s6, v[2:3]
	v_add_u32_e32 v6, 20, v8
	v_mad_i64_i32 v[6:7], s[26:27], v6, s6, v[2:3]
	global_load_dwordx4 v[62:65], v[4:5], off nt
	global_load_dwordx4 v[38:41], v[6:7], off nt
	v_add_u32_e32 v4, 24, v8
	v_mad_i64_i32 v[4:5], s[26:27], v4, s6, v[2:3]
	v_add_u32_e32 v6, 28, v8
	v_mad_i64_i32 v[6:7], s[26:27], v6, s6, v[2:3]
	global_load_dwordx4 v[58:61], v[4:5], off nt
	global_load_dwordx4 v[26:29], v[6:7], off nt
	v_add_u32_e32 v4, 32, v8
	v_mad_i64_i32 v[4:5], s[26:27], v4, s6, v[2:3]
	v_add_u32_e32 v6, 36, v8
	v_mad_i64_i32 v[6:7], s[26:27], v6, s6, v[2:3]
	global_load_dwordx4 v[50:53], v[4:5], off nt
	global_load_dwordx4 v[22:25], v[6:7], off nt
	v_add_u32_e32 v4, 40, v8
	v_mad_i64_i32 v[4:5], s[26:27], v4, s6, v[2:3]
	v_add_u32_e32 v6, 44, v8
	v_mad_i64_i32 v[6:7], s[26:27], v6, s6, v[2:3]
	global_load_dwordx4 v[42:45], v[4:5], off nt
	global_load_dwordx4 v[18:21], v[6:7], off nt
	v_add_u32_e32 v4, 48, v8
	v_mad_i64_i32 v[4:5], s[26:27], v4, s6, v[2:3]
	v_add_u32_e32 v6, 52, v8
	v_mad_i64_i32 v[6:7], s[26:27], v6, s6, v[2:3]
	global_load_dwordx4 v[30:33], v[4:5], off nt
	global_load_dwordx4 v[10:13], v[6:7], off nt
	v_add_u32_e32 v4, 56, v8
	v_mad_i64_i32 v[4:5], s[26:27], v4, s6, v[2:3]
	v_add_u32_e32 v6, 60, v8
	v_mad_i64_i32 v[2:3], s[26:27], v6, s6, v[2:3]
	global_load_dwordx4 v[34:37], v[4:5], off nt
	global_load_dwordx4 v[14:17], v[2:3], off nt
	v_readlane_b32 s6, v242, 58
	v_readlane_b32 s7, v242, 59
	s_andn2_b64 vcc, exec, s[6:7]
	s_lshl_b32 s24, s24, 6
	s_cbranch_vccnz .LBB0_190
	s_lshl_b32 s84, s25, 2
	v_lshl_add_u64 v[6:7], v[90:91], 0, s[84:85]
	global_load_dwordx4 v[2:5], v[6:7], off offset:16 nt
	s_nop 0
	global_load_dwordx4 v[6:9], v[6:7], off nt
	s_branch .LBB0_191

; #define GAS __attribute__((address_space(1)))
; #define LAS __attribute__((address_space(3)))
; template <int GU>
; __device__ __forceinline__ void p0_transpose_item(const float* W, int N, const float* kscale, bf16* WT, int ldt, int koff, LAS float* scr, int item, int lane) {
;     const int nblk = N / 64, kb = item / nblk, nb = item % nblk, k0 = 64 * kb, n0 = 64 * nb;
;     const int q = lane >> 4, cc = lane & 15;
;     f32x4 v[16];
; #pragma unroll
;     for (int i = 0; i < 16; ++i) v[i] = *(const GAS f32x4*)(W + (size_t)(k0 + 4 * i + q) * N + n0 + 4 * cc);
;     const int c = lane & 7;
;     f32x4 s0 = (f32x4){1.f, 1.f, 1.f, 1.f}, s1 = s0;
;     if (kscale) { s0 = *(const GAS f32x4*)(kscale + k0 + 8 * c); s1 = *(const GAS f32x4*)(kscale + k0 + 8 * c + 4); }
; #pragma unroll
;     for (int i = 0; i < 16; ++i) { LAS float* d = scr + (4 * i + q) * TR_PITCH + 4 * cc; d[0] = v[i].x; d[1] = v[i].y; d[2] = v[i].z; d[3] = v[i].w; }
.LBB0_193:
	s_andn2_b64 vcc, exec, s[36:37]
	s_cbranch_vccnz .LBB0_195
	s_add_i32 s24, s23, 0xfffff840
	s_lshl_b32 s25, s24, 2
	s_lshl_b32 s24, s24, 6
	s_and_b32 s26, s25, 0xfc0
	s_and_b32 s24, s24, 0x3c0
	v_add_u32_e32 v2, s26, v102
	v_add_u32_e32 v4, s26, v103
	s_lshl_b32 s84, s24, 2
	v_ashrrev_i32_e32 v3, 31, v2
	v_ashrrev_i32_e32 v5, 31, v4
	v_lshl_add_u64 v[62:63], v[94:95], 0, s[84:85]
	v_lshlrev_b64 v[2:3], 12, v[2:3]
	v_lshlrev_b64 v[4:5], 12, v[4:5]
	v_lshl_add_u64 v[2:3], v[62:63], 0, v[2:3]
	v_lshl_add_u64 v[6:7], v[62:63], 0, v[4:5]
	v_add_u32_e32 v10, s26, v104
	v_add_u32_e32 v12, s26, v105
	global_load_dwordx4 v[2:5], v[2:3], off nt
	s_nop 0
	global_load_dwordx4 v[6:9], v[6:7], off nt
	v_ashrrev_i32_e32 v11, 31, v10
	v_ashrrev_i32_e32 v13, 31, v12
	v_lshlrev_b64 v[10:11], 12, v[10:11]
	v_lshlrev_b64 v[12:13], 12, v[12:13]
	v_lshl_add_u64 v[10:11], v[62:63], 0, v[10:11]
	v_lshl_add_u64 v[14:15], v[62:63], 0, v[12:13]
	global_load_dwordx4 v[10:13], v[10:11], off nt
	s_nop 0
	global_load_dwordx4 v[14:17], v[14:15], off nt
	v_add_u32_e32 v18, s26, v106
	v_add_u32_e32 v20, s26, v107
	v_ashrrev_i32_e32 v19, 31, v18
	v_ashrrev_i32_e32 v21, 31, v20
	v_lshlrev_b64 v[18:19], 12, v[18:19]
	v_lshlrev_b64 v[20:21], 12, v[20:21]
	v_lshl_add_u64 v[18:19], v[62:63], 0, v[18:19]
	v_lshl_add_u64 v[22:23], v[62:63], 0, v[20:21]
	global_load_dwordx4 v[18:21], v[18:19], off nt
	s_nop 0
	global_load_dwordx4 v[22:25], v[22:23], off nt
	v_add_u32_e32 v26, s26, v108
	v_add_u32_e32 v28, s26, v109
	v_ashrrev_i32_e32 v27, 31, v26
	v_ashrrev_i32_e32 v29, 31, v28
	v_lshlrev_b64 v[26:27], 12, v[26:27]
	v_lshlrev_b64 v[28:29], 12, v[28:29]
	v_lshl_add_u64 v[26:27], v[62:63], 0, v[26:27]
	v_lshl_add_u64 v[30:31], v[62:63], 0, v[28:29]
	global_load_dwordx4 v[26:29], v[26:27], off nt
	s_nop 0
	global_load_dwordx4 v[30:33], v[30:31], off nt
	v_add_u32_e32 v34, s26, v110
	v_add_u32_e32 v36, s26, v111
	v_ashrrev_i32_e32 v35, 31, v34
	v_ashrrev_i32_e32 v37, 31, v36
	v_lshlrev_b64 v[34:35], 12, v[34:35]
	v_lshlrev_b64 v[36:37], 12, v[36:37]
	v_lshl_add_u64 v[34:35], v[62:63], 0, v[34:35]
	v_lshl_add_u64 v[38:39], v[62:63], 0, v[36:37]
	global_load_dwordx4 v[34:37], v[34:35], off nt
	s_nop 0
	global_load_dwordx4 v[38:41], v[38:39], off nt
	v_add_u32_e32 v42, s26, v112
	v_add_u32_e32 v44, s26, v113
	v_ashrrev_i32_e32 v43, 31, v42
	v_ashrrev_i32_e32 v45, 31, v44
	v_lshlrev_b64 v[42:43], 12, v[42:43]
	v_lshlrev_b64 v[44:45], 12, v[44:45]
	v_lshl_add_u64 v[42:43], v[62:63], 0, v[42:43]
	v_lshl_add_u64 v[46:47], v[62:63], 0, v[44:45]
	global_load_dwordx4 v[42:45], v[42:43], off nt
	s_nop 0
	global_load_dwordx4 v[46:49], v[46:47], off nt
	v_add_u32_e32 v50, s26, v114
	v_add_u32_e32 v52, s26, v115
	v_ashrrev_i32_e32 v51, 31, v50
	v_ashrrev_i32_e32 v53, 31, v52
	v_lshlrev_b64 v[50:51], 12, v[50:51]
	v_lshlrev_b64 v[52:53], 12, v[52:53]
	v_lshl_add_u64 v[50:51], v[62:63], 0, v[50:51]
	v_lshl_add_u64 v[54:55], v[62:63], 0, v[52:53]
	v_add_u32_e32 v58, s26, v116
	global_load_dwordx4 v[50:53], v[50:51], off nt
	s_nop 0
	global_load_dwordx4 v[54:57], v[54:55], off nt
	v_ashrrev_i32_e32 v59, 31, v58
	s_or_b32 s25, s25, 60
	v_lshlrev_b64 v[58:59], 12, v[58:59]
	v_add_u32_e32 v64, s25, v102
	v_lshl_add_u64 v[58:59], v[62:63], 0, v[58:59]
	v_ashrrev_i32_e32 v65, 31, v64
	global_load_dwordx4 v[58:61], v[58:59], off nt
	v_lshlrev_b64 v[64:65], 12, v[64:65]
	v_lshl_add_u64 v[62:63], v[62:63], 0, v[64:65]
	global_load_dwordx4 v[62:65], v[62:63], off nt
	s_lshl_b32 s84, s26, 1
	s_waitcnt vmcnt(0)
	ds_write2_b32 v117, v2, v3 offset1:1
	ds_write2_b32 v117, v4, v5 offset0:2 offset1:3
	v_add_u32_e32 v2, 0x410, v117
	ds_write2_b32 v2, v6, v7 offset1:1
	v_add_u32_e32 v2, 0x418, v117
	ds_write2_b32 v2, v8, v9 offset1:1
	v_add_u32_e32 v2, 0x820, v117
	ds_write2_b32 v2, v10, v11 offset1:1
	v_add_u32_e32 v2, 0x828, v117
	ds_write2_b32 v2, v12, v13 offset1:1
	v_add_u32_e32 v2, 0xc30, v117
	ds_write2_b32 v2, v14, v15 offset1:1
	v_add_u32_e32 v2, 0xc38, v117
	ds_write2_b32 v2, v16, v17 offset1:1
	v_add_u32_e32 v2, 0x1040, v117
	ds_write2_b32 v2, v18, v19 offset1:1
	v_add_u32_e32 v2, 0x1048, v117
	ds_write2_b32 v2, v20, v21 offset1:1
	v_add_u32_e32 v2, 0x1450, v117
	ds_write2_b32 v2, v22, v23 offset1:1
	v_add_u32_e32 v2, 0x1458, v117
	ds_write2_b32 v2, v24, v25 offset1:1
	v_add_u32_e32 v2, 0x1860, v117
	v_add_u32_e32 v24, s24, v118
	ds_write2_b32 v2, v26, v27 offset1:1
	v_add_u32_e32 v2, 0x1868, v117
	ds_write2_b32 v2, v28, v29 offset1:1
	v_add_u32_e32 v2, 0x1c70, v117
	ds_write2_b32 v2, v30, v31 offset1:1
	v_add_u32_e32 v2, 0x1c78, v117
	ds_write2_b32 v2, v32, v33 offset1:1
	v_add_u32_e32 v2, 0x2080, v117
	v_add_u32_e32 v26, 0x400, v119
	ds_write2_b32 v2, v34, v35 offset1:1
	v_add_u32_e32 v2, 0x2088, v117
	ds_write2_b32 v2, v36, v37 offset1:1
	v_add_u32_e32 v2, 0x2490, v117
	ds_write2_b32 v2, v38, v39 offset1:1
	v_add_u32_e32 v2, 0x2498, v117
	ds_write2_b32 v2, v40, v41 offset1:1
	v_add_u32_e32 v2, 0x28a0, v117
	v_ashrrev_i32_e32 v25, 31, v24
	ds_write2_b32 v2, v42, v43 offset1:1
	v_add_u32_e32 v2, 0x28a8, v117
	ds_write2_b32 v2, v44, v45 offset1:1
	v_add_u32_e32 v2, 0x2cb0, v117
	ds_write2_b32 v2, v46, v47 offset1:1
	v_add_u32_e32 v2, 0x2cb8, v117
	ds_write2_b32 v2, v48, v49 offset1:1
	v_add_u32_e32 v2, 0x30c0, v117
	v_lshl_add_u64 v[22:23], v[78:79], 0, s[84:85]
	v_lshlrev_b64 v[24:25], 11, v[24:25]
	ds_write2_b32 v2, v50, v51 offset1:1
	v_add_u32_e32 v2, 0x30c8, v117
	ds_write2_b32 v2, v52, v53 offset1:1
	v_add_u32_e32 v2, 0x34d0, v117
	ds_write2_b32 v2, v54, v55 offset1:1
	v_add_u32_e32 v2, 0x34d8, v117
	ds_write2_b32 v2, v56, v57 offset1:1
	v_add_u32_e32 v2, 0x38e0, v117
	ds_write2_b32 v2, v58, v59 offset1:1
	v_add_u32_e32 v2, 0x38e8, v117
	ds_write2_b32 v2, v60, v61 offset1:1
	v_add_u32_e32 v2, 0x3cf0, v117
	ds_write2_b32 v2, v62, v63 offset1:1
	v_add_u32_e32 v2, 0x3cf8, v117
	ds_write2_b32 v2, v64, v65 offset1:1
	s_waitcnt lgkmcnt(0)
; #define GAS __attribute__((address_space(1)))
; #define LAS __attribute__((address_space(3)))
; #define LDS_WAIT() asm volatile("s_waitcnt lgkmcnt(0)" ::: "memory")
; __device__ __forceinline__ unsigned pk2(float lo, float hi) { f32x2p v = {lo, hi}; bf16x2p b = __builtin_convertvector(v, bf16x2p); return __builtin_bit_cast(unsigned, b); }
; template <int GU>
; __device__ __forceinline__ void p0_transpose_item(const float* W, int N, const float* kscale, bf16* WT, int ldt, int koff, LAS float* scr, int item, int lane) {
;     ...
;     LDS_WAIT(); asm volatile("" ::: "memory");
; #pragma unroll
;     for (int j = 0; j < 8; ++j) { const int n = (lane >> 3) + 8 * j; const LAS float* s = scr + (8 * c) * TR_PITCH + n;
;         v4u o; o.x = pk2(s[0 * TR_PITCH] * s0.x, s[1 * TR_PITCH] * s0.y); o.y = pk2(s[2 * TR_PITCH] * s0.z, s[3 * TR_PITCH] * s0.w);
;         o.z = pk2(s[4 * TR_PITCH] * s1.x, s[5 * TR_PITCH] * s1.y); o.w = pk2(s[6 * TR_PITCH] * s1.z, s[7 * TR_PITCH] * s1.w);
;         const int ng = n0 + n; int drow;
;         if (GU == 0) drow = ng;
;         else if (GU == 3) { const int gsel = (ng >= 2304) ? 1 : 0, j = ng - 1280 - 1024 * gsel; drow = (ng < 1280) ? ng : (1280 + 256 * (j >> 7) + 128 * gsel + (j & 127)); }
;         else drow = 256 * (ng >> 7) + (GU - 1) * 128 + (ng & 127);
;         *(GAS v4u*)(WT + (size_t)drow * ldt + koff + k0 + 8 * c) = o; }
;     LDS_WAIT(); asm volatile("" ::: "memory");
	ds_read2_b32 v[6:7], v119 offset0:65 offset1:73
	ds_read2_b32 v[8:9], v119 offset1:8
	ds_read2_b32 v[10:11], v119 offset0:130 offset1:138
	ds_read2_b32 v[12:13], v119 offset0:195 offset1:203
	ds_read2_b32 v[14:15], v26 offset0:4 offset1:12
	ds_read2_b32 v[16:17], v26 offset0:69 offset1:77
	ds_read2_b32 v[18:19], v26 offset0:134 offset1:142
	ds_read2_b32 v[20:21], v26 offset0:199 offset1:207
	v_lshl_add_u64 v[24:25], v[22:23], 0, v[24:25]
	s_waitcnt lgkmcnt(6)
	v_cvt_pk_bf16_f32 v2, v8, v6
	s_waitcnt lgkmcnt(2)
	v_cvt_pk_bf16_f32 v4, v14, v16
	v_cvt_pk_bf16_f32 v3, v10, v12
	s_waitcnt lgkmcnt(0)
	v_cvt_pk_bf16_f32 v5, v18, v20
	v_add_u32_e32 v6, s24, v120
	global_store_dwordx4 v[24:25], v[2:5], off sc1
	s_nop 1
	v_cvt_pk_bf16_f32 v2, v9, v7
	v_ashrrev_i32_e32 v7, 31, v6
	v_cvt_pk_bf16_f32 v3, v11, v13
	v_cvt_pk_bf16_f32 v4, v15, v17
	v_cvt_pk_bf16_f32 v5, v19, v21
	v_lshlrev_b64 v[6:7], 11, v[6:7]
	ds_read2_b32 v[8:9], v119 offset0:81 offset1:89
	ds_read2_b32 v[10:11], v119 offset0:16 offset1:24
	ds_read2_b32 v[12:13], v119 offset0:146 offset1:154
	ds_read2_b32 v[14:15], v119 offset0:211 offset1:219
	ds_read2_b32 v[16:17], v26 offset0:20 offset1:28
	ds_read2_b32 v[18:19], v26 offset0:85 offset1:93
	ds_read2_b32 v[20:21], v26 offset0:150 offset1:158
	ds_read2_b32 v[24:25], v26 offset0:215 offset1:223
	v_lshl_add_u64 v[6:7], v[22:23], 0, v[6:7]
	global_store_dwordx4 v[6:7], v[2:5], off sc1
	v_add_u32_e32 v6, s24, v121
	v_ashrrev_i32_e32 v7, 31, v6
	v_lshlrev_b64 v[6:7], 11, v[6:7]
	s_waitcnt lgkmcnt(6)
	v_cvt_pk_bf16_f32 v2, v10, v8
	s_waitcnt lgkmcnt(4)
	v_cvt_pk_bf16_f32 v3, v12, v14
	s_waitcnt lgkmcnt(2)
	v_cvt_pk_bf16_f32 v4, v16, v18
	s_waitcnt lgkmcnt(0)
	v_cvt_pk_bf16_f32 v5, v20, v24
	v_lshl_add_u64 v[6:7], v[22:23], 0, v[6:7]
	global_store_dwordx4 v[6:7], v[2:5], off sc1
	v_add_u32_e32 v6, s24, v122
	v_ashrrev_i32_e32 v7, 31, v6
	v_cvt_pk_bf16_f32 v2, v11, v9
	v_cvt_pk_bf16_f32 v3, v13, v15
	v_cvt_pk_bf16_f32 v4, v17, v19
	v_cvt_pk_bf16_f32 v5, v21, v25
	v_lshlrev_b64 v[6:7], 11, v[6:7]
	ds_read2_b32 v[8:9], v119 offset0:32 offset1:40
	ds_read2_b32 v[10:11], v119 offset0:97 offset1:105
	ds_read2_b32 v[12:13], v119 offset0:162 offset1:170
	ds_read2_b32 v[14:15], v119 offset0:227 offset1:235
	ds_read2_b32 v[16:17], v26 offset0:36 offset1:44
	ds_read2_b32 v[18:19], v26 offset0:101 offset1:109
	ds_read2_b32 v[20:21], v26 offset0:166 offset1:174
	ds_read2_b32 v[24:25], v26 offset0:231 offset1:239
	v_lshl_add_u64 v[6:7], v[22:23], 0, v[6:7]
	global_store_dwordx4 v[6:7], v[2:5], off sc1
	v_add_u32_e32 v6, s24, v123
	v_ashrrev_i32_e32 v7, 31, v6
	v_lshlrev_b64 v[6:7], 11, v[6:7]
	s_waitcnt lgkmcnt(6)
	v_cvt_pk_bf16_f32 v2, v8, v10
	s_waitcnt lgkmcnt(4)
	v_cvt_pk_bf16_f32 v3, v12, v14
	s_waitcnt lgkmcnt(2)
	v_cvt_pk_bf16_f32 v4, v16, v18
	s_waitcnt lgkmcnt(0)
	v_cvt_pk_bf16_f32 v5, v20, v24
	v_lshl_add_u64 v[6:7], v[22:23], 0, v[6:7]
	global_store_dwordx4 v[6:7], v[2:5], off sc1
	v_add_u32_e32 v6, s24, v124
	v_ashrrev_i32_e32 v7, 31, v6
	v_cvt_pk_bf16_f32 v2, v9, v11
	v_cvt_pk_bf16_f32 v3, v13, v15
	v_cvt_pk_bf16_f32 v4, v17, v19
	v_cvt_pk_bf16_f32 v5, v21, v25
	v_lshlrev_b64 v[6:7], 11, v[6:7]
	ds_read2_b32 v[8:9], v119 offset0:48 offset1:56
	ds_read2_b32 v[10:11], v119 offset0:113 offset1:121
	ds_read2_b32 v[12:13], v119 offset0:178 offset1:186
	ds_read2_b32 v[14:15], v119 offset0:243 offset1:251
	ds_read2_b32 v[16:17], v26 offset0:52 offset1:60
	ds_read2_b32 v[18:19], v26 offset0:117 offset1:125
	ds_read2_b32 v[20:21], v26 offset0:182 offset1:190
	ds_read2_b32 v[24:25], v26 offset0:247 offset1:255
	v_lshl_add_u64 v[6:7], v[22:23], 0, v[6:7]
	global_store_dwordx4 v[6:7], v[2:5], off sc1
	v_add_u32_e32 v6, s24, v125
	v_ashrrev_i32_e32 v7, 31, v6
	v_lshlrev_b64 v[6:7], 11, v[6:7]
	s_waitcnt lgkmcnt(6)
	v_cvt_pk_bf16_f32 v2, v8, v10
	s_waitcnt lgkmcnt(4)
	v_cvt_pk_bf16_f32 v3, v12, v14
	s_waitcnt lgkmcnt(2)
	v_cvt_pk_bf16_f32 v4, v16, v18
	s_waitcnt lgkmcnt(0)
	v_cvt_pk_bf16_f32 v5, v20, v24
	v_lshl_add_u64 v[6:7], v[22:23], 0, v[6:7]
	global_store_dwordx4 v[6:7], v[2:5], off sc1
	v_add_u32_e32 v6, s24, v126
	v_ashrrev_i32_e32 v7, 31, v6
	v_lshlrev_b64 v[6:7], 11, v[6:7]
	v_cvt_pk_bf16_f32 v2, v9, v11
	v_cvt_pk_bf16_f32 v3, v13, v15
	v_cvt_pk_bf16_f32 v4, v17, v19
	v_cvt_pk_bf16_f32 v5, v21, v25
	v_lshl_add_u64 v[6:7], v[22:23], 0, v[6:7]
	global_store_dwordx4 v[6:7], v[2:5], off sc1
	s_waitcnt lgkmcnt(0)

; #define GAS __attribute__((address_space(1)))
; #define LAS __attribute__((address_space(3)))
; template <int GU>
; __device__ __forceinline__ void p0_transpose_item(const float* W, int N, const float* kscale, bf16* WT, int ldt, int koff, LAS float* scr, int item, int lane) {
;     const int nblk = N / 64, kb = item / nblk, nb = item % nblk, k0 = 64 * kb, n0 = 64 * nb;
;     const int q = lane >> 4, cc = lane & 15;
;     f32x4 v[16];
; #pragma unroll
;     for (int i = 0; i < 16; ++i) v[i] = *(const GAS f32x4*)(W + (size_t)(k0 + 4 * i + q) * N + n0 + 4 * cc);
;     const int c = lane & 7;
;     f32x4 s0 = (f32x4){1.f, 1.f, 1.f, 1.f}, s1 = s0;
;     if (kscale) { s0 = *(const GAS f32x4*)(kscale + k0 + 8 * c); s1 = *(const GAS f32x4*)(kscale + k0 + 8 * c + 4); }
; #pragma unroll
;     for (int i = 0; i < 16; ++i) { LAS float* d = scr + (4 * i + q) * TR_PITCH + 4 * cc; d[0] = v[i].x; d[1] = v[i].y; d[2] = v[i].z; d[3] = v[i].w; }
.LBB0_196:
	s_andn2_b64 vcc, exec, s[36:37]
	s_cbranch_vccnz .LBB0_198
	s_add_i32 s24, s23, 0xfffff8c0
	s_lshl_b32 s25, s24, 2
	s_lshl_b32 s24, s24, 6
	s_and_b32 s26, s25, 0xfc0
	s_and_b32 s24, s24, 0x3c0
	v_add_u32_e32 v2, s26, v102
	v_add_u32_e32 v4, s26, v103
	s_lshl_b32 s84, s24, 2
	v_ashrrev_i32_e32 v3, 31, v2
	v_ashrrev_i32_e32 v5, 31, v4
	v_lshl_add_u64 v[62:63], v[96:97], 0, s[84:85]
	v_lshlrev_b64 v[2:3], 12, v[2:3]
	v_lshlrev_b64 v[4:5], 12, v[4:5]
	v_lshl_add_u64 v[2:3], v[62:63], 0, v[2:3]
	v_lshl_add_u64 v[6:7], v[62:63], 0, v[4:5]
	v_add_u32_e32 v10, s26, v104
	v_add_u32_e32 v12, s26, v105
	global_load_dwordx4 v[2:5], v[2:3], off nt
	s_nop 0
	global_load_dwordx4 v[6:9], v[6:7], off nt
	v_ashrrev_i32_e32 v11, 31, v10
	v_ashrrev_i32_e32 v13, 31, v12
	v_lshlrev_b64 v[10:11], 12, v[10:11]
	v_lshlrev_b64 v[12:13], 12, v[12:13]
	v_lshl_add_u64 v[10:11], v[62:63], 0, v[10:11]
	v_lshl_add_u64 v[14:15], v[62:63], 0, v[12:13]
	global_load_dwordx4 v[10:13], v[10:11], off nt
	s_nop 0
	global_load_dwordx4 v[14:17], v[14:15], off nt
	v_add_u32_e32 v18, s26, v106
	v_add_u32_e32 v20, s26, v107
	v_ashrrev_i32_e32 v19, 31, v18
	v_ashrrev_i32_e32 v21, 31, v20
	v_lshlrev_b64 v[18:19], 12, v[18:19]
	v_lshlrev_b64 v[20:21], 12, v[20:21]
	v_lshl_add_u64 v[18:19], v[62:63], 0, v[18:19]
	v_lshl_add_u64 v[22:23], v[62:63], 0, v[20:21]
	global_load_dwordx4 v[18:21], v[18:19], off nt
	s_nop 0
	global_load_dwordx4 v[22:25], v[22:23], off nt
	v_add_u32_e32 v26, s26, v108
	v_add_u32_e32 v28, s26, v109
	v_ashrrev_i32_e32 v27, 31, v26
	v_ashrrev_i32_e32 v29, 31, v28
	v_lshlrev_b64 v[26:27], 12, v[26:27]
	v_lshlrev_b64 v[28:29], 12, v[28:29]
	v_lshl_add_u64 v[26:27], v[62:63], 0, v[26:27]
	v_lshl_add_u64 v[30:31], v[62:63], 0, v[28:29]
	global_load_dwordx4 v[26:29], v[26:27], off nt
	s_nop 0
	global_load_dwordx4 v[30:33], v[30:31], off nt
	v_add_u32_e32 v34, s26, v110
	v_add_u32_e32 v36, s26, v111
	v_ashrrev_i32_e32 v35, 31, v34
	v_ashrrev_i32_e32 v37, 31, v36
	v_lshlrev_b64 v[34:35], 12, v[34:35]
	v_lshlrev_b64 v[36:37], 12, v[36:37]
	v_lshl_add_u64 v[34:35], v[62:63], 0, v[34:35]
	v_lshl_add_u64 v[38:39], v[62:63], 0, v[36:37]
	global_load_dwordx4 v[34:37], v[34:35], off nt
	s_nop 0
	global_load_dwordx4 v[38:41], v[38:39], off nt
	v_add_u32_e32 v42, s26, v112
	v_add_u32_e32 v44, s26, v113
	v_ashrrev_i32_e32 v43, 31, v42
	v_ashrrev_i32_e32 v45, 31, v44
	v_lshlrev_b64 v[42:43], 12, v[42:43]
	v_lshlrev_b64 v[44:45], 12, v[44:45]
	v_lshl_add_u64 v[42:43], v[62:63], 0, v[42:43]
	v_lshl_add_u64 v[46:47], v[62:63], 0, v[44:45]
	global_load_dwordx4 v[42:45], v[42:43], off nt
	s_nop 0
	global_load_dwordx4 v[46:49], v[46:47], off nt
	v_add_u32_e32 v50, s26, v114
	v_add_u32_e32 v52, s26, v115
	v_ashrrev_i32_e32 v51, 31, v50
	v_ashrrev_i32_e32 v53, 31, v52
	v_lshlrev_b64 v[50:51], 12, v[50:51]
	v_lshlrev_b64 v[52:53], 12, v[52:53]
	v_lshl_add_u64 v[50:51], v[62:63], 0, v[50:51]
	v_lshl_add_u64 v[54:55], v[62:63], 0, v[52:53]
	v_add_u32_e32 v58, s26, v116
	global_load_dwordx4 v[50:53], v[50:51], off nt
	s_nop 0
	global_load_dwordx4 v[54:57], v[54:55], off nt
	v_ashrrev_i32_e32 v59, 31, v58
	s_or_b32 s25, s25, 60
	v_lshlrev_b64 v[58:59], 12, v[58:59]
	v_add_u32_e32 v64, s25, v102
	v_lshl_add_u64 v[58:59], v[62:63], 0, v[58:59]
	v_ashrrev_i32_e32 v65, 31, v64
	global_load_dwordx4 v[58:61], v[58:59], off nt
	v_lshlrev_b64 v[64:65], 12, v[64:65]
	v_lshl_add_u64 v[62:63], v[62:63], 0, v[64:65]
	global_load_dwordx4 v[62:65], v[62:63], off nt
	s_lshl_b32 s84, s26, 1
	s_waitcnt vmcnt(0)
	ds_write2_b32 v117, v2, v3 offset1:1
	ds_write2_b32 v117, v4, v5 offset0:2 offset1:3
	v_add_u32_e32 v2, 0x410, v117
	ds_write2_b32 v2, v6, v7 offset1:1
	v_add_u32_e32 v2, 0x418, v117
	ds_write2_b32 v2, v8, v9 offset1:1
	v_add_u32_e32 v2, 0x820, v117
	ds_write2_b32 v2, v10, v11 offset1:1
	v_add_u32_e32 v2, 0x828, v117
	ds_write2_b32 v2, v12, v13 offset1:1
	v_add_u32_e32 v2, 0xc30, v117
	ds_write2_b32 v2, v14, v15 offset1:1
	v_add_u32_e32 v2, 0xc38, v117
	ds_write2_b32 v2, v16, v17 offset1:1
	v_add_u32_e32 v2, 0x1040, v117
	ds_write2_b32 v2, v18, v19 offset1:1
	v_add_u32_e32 v2, 0x1048, v117
	ds_write2_b32 v2, v20, v21 offset1:1
	v_add_u32_e32 v2, 0x1450, v117
	ds_write2_b32 v2, v22, v23 offset1:1
	v_add_u32_e32 v2, 0x1458, v117
	ds_write2_b32 v2, v24, v25 offset1:1
	v_add_u32_e32 v2, 0x1860, v117
	v_add_u32_e32 v24, s24, v118
	ds_write2_b32 v2, v26, v27 offset1:1
	v_add_u32_e32 v2, 0x1868, v117
	ds_write2_b32 v2, v28, v29 offset1:1
	v_add_u32_e32 v2, 0x1c70, v117
	ds_write2_b32 v2, v30, v31 offset1:1
	v_add_u32_e32 v2, 0x1c78, v117
	ds_write2_b32 v2, v32, v33 offset1:1
	v_add_u32_e32 v2, 0x2080, v117
	v_add_u32_e32 v26, 0x400, v119
	ds_write2_b32 v2, v34, v35 offset1:1
	v_add_u32_e32 v2, 0x2088, v117
	ds_write2_b32 v2, v36, v37 offset1:1
	v_add_u32_e32 v2, 0x2490, v117
	ds_write2_b32 v2, v38, v39 offset1:1
	v_add_u32_e32 v2, 0x2498, v117
	ds_write2_b32 v2, v40, v41 offset1:1
	v_add_u32_e32 v2, 0x28a0, v117
	v_ashrrev_i32_e32 v25, 31, v24
	ds_write2_b32 v2, v42, v43 offset1:1
	v_add_u32_e32 v2, 0x28a8, v117
	ds_write2_b32 v2, v44, v45 offset1:1
	v_add_u32_e32 v2, 0x2cb0, v117
	ds_write2_b32 v2, v46, v47 offset1:1
	v_add_u32_e32 v2, 0x2cb8, v117
	ds_write2_b32 v2, v48, v49 offset1:1
	v_add_u32_e32 v2, 0x30c0, v117
	v_lshl_add_u64 v[22:23], v[80:81], 0, s[84:85]
	v_lshlrev_b64 v[24:25], 11, v[24:25]
	ds_write2_b32 v2, v50, v51 offset1:1
	v_add_u32_e32 v2, 0x30c8, v117
	ds_write2_b32 v2, v52, v53 offset1:1
	v_add_u32_e32 v2, 0x34d0, v117
	ds_write2_b32 v2, v54, v55 offset1:1
	v_add_u32_e32 v2, 0x34d8, v117
	ds_write2_b32 v2, v56, v57 offset1:1
	v_add_u32_e32 v2, 0x38e0, v117
	ds_write2_b32 v2, v58, v59 offset1:1
	v_add_u32_e32 v2, 0x38e8, v117
	ds_write2_b32 v2, v60, v61 offset1:1
	v_add_u32_e32 v2, 0x3cf0, v117
	ds_write2_b32 v2, v62, v63 offset1:1
	v_add_u32_e32 v2, 0x3cf8, v117
	ds_write2_b32 v2, v64, v65 offset1:1
	s_waitcnt lgkmcnt(0)
; #define GAS __attribute__((address_space(1)))
; #define LAS __attribute__((address_space(3)))
; #define LDS_WAIT() asm volatile("s_waitcnt lgkmcnt(0)" ::: "memory")
; __device__ __forceinline__ unsigned pk2(float lo, float hi) { f32x2p v = {lo, hi}; bf16x2p b = __builtin_convertvector(v, bf16x2p); return __builtin_bit_cast(unsigned, b); }
; template <int GU>
; __device__ __forceinline__ void p0_transpose_item(const float* W, int N, const float* kscale, bf16* WT, int ldt, int koff, LAS float* scr, int item, int lane) {
;     ...
;     LDS_WAIT(); asm volatile("" ::: "memory");
; #pragma unroll
;     for (int j = 0; j < 8; ++j) { const int n = (lane >> 3) + 8 * j; const LAS float* s = scr + (8 * c) * TR_PITCH + n;
;         v4u o; o.x = pk2(s[0 * TR_PITCH] * s0.x, s[1 * TR_PITCH] * s0.y); o.y = pk2(s[2 * TR_PITCH] * s0.z, s[3 * TR_PITCH] * s0.w);
;         o.z = pk2(s[4 * TR_PITCH] * s1.x, s[5 * TR_PITCH] * s1.y); o.w = pk2(s[6 * TR_PITCH] * s1.z, s[7 * TR_PITCH] * s1.w);
;         const int ng = n0 + n; int drow;
;         if (GU == 0) drow = ng;
;         else if (GU == 3) { const int gsel = (ng >= 2304) ? 1 : 0, j = ng - 1280 - 1024 * gsel; drow = (ng < 1280) ? ng : (1280 + 256 * (j >> 7) + 128 * gsel + (j & 127)); }
;         else drow = 256 * (ng >> 7) + (GU - 1) * 128 + (ng & 127);
;         *(GAS v4u*)(WT + (size_t)drow * ldt + koff + k0 + 8 * c) = o; }
;     LDS_WAIT(); asm volatile("" ::: "memory");
	ds_read2_b32 v[6:7], v119 offset0:65 offset1:73
	ds_read2_b32 v[8:9], v119 offset1:8
	ds_read2_b32 v[10:11], v119 offset0:130 offset1:138
	ds_read2_b32 v[12:13], v119 offset0:195 offset1:203
	ds_read2_b32 v[14:15], v26 offset0:4 offset1:12
	ds_read2_b32 v[16:17], v26 offset0:69 offset1:77
	ds_read2_b32 v[18:19], v26 offset0:134 offset1:142
	ds_read2_b32 v[20:21], v26 offset0:199 offset1:207
	v_lshl_add_u64 v[24:25], v[22:23], 0, v[24:25]
	s_waitcnt lgkmcnt(6)
	v_cvt_pk_bf16_f32 v2, v8, v6
	s_waitcnt lgkmcnt(2)
	v_cvt_pk_bf16_f32 v4, v14, v16
	v_cvt_pk_bf16_f32 v3, v10, v12
	s_waitcnt lgkmcnt(0)
	v_cvt_pk_bf16_f32 v5, v18, v20
	v_add_u32_e32 v6, s24, v120
	global_store_dwordx4 v[24:25], v[2:5], off sc1
	s_nop 1
	v_cvt_pk_bf16_f32 v2, v9, v7
	v_ashrrev_i32_e32 v7, 31, v6
	v_cvt_pk_bf16_f32 v3, v11, v13
	v_cvt_pk_bf16_f32 v4, v15, v17
	v_cvt_pk_bf16_f32 v5, v19, v21
	v_lshlrev_b64 v[6:7], 11, v[6:7]
	ds_read2_b32 v[8:9], v119 offset0:81 offset1:89
	ds_read2_b32 v[10:11], v119 offset0:16 offset1:24
	ds_read2_b32 v[12:13], v119 offset0:146 offset1:154
	ds_read2_b32 v[14:15], v119 offset0:211 offset1:219
	ds_read2_b32 v[16:17], v26 offset0:20 offset1:28
	ds_read2_b32 v[18:19], v26 offset0:85 offset1:93
	ds_read2_b32 v[20:21], v26 offset0:150 offset1:158
	ds_read2_b32 v[24:25], v26 offset0:215 offset1:223
	v_lshl_add_u64 v[6:7], v[22:23], 0, v[6:7]
	global_store_dwordx4 v[6:7], v[2:5], off sc1
	v_add_u32_e32 v6, s24, v121
	v_ashrrev_i32_e32 v7, 31, v6
	v_lshlrev_b64 v[6:7], 11, v[6:7]
	s_waitcnt lgkmcnt(6)
	v_cvt_pk_bf16_f32 v2, v10, v8
	s_waitcnt lgkmcnt(4)
	v_cvt_pk_bf16_f32 v3, v12, v14
	s_waitcnt lgkmcnt(2)
	v_cvt_pk_bf16_f32 v4, v16, v18
	s_waitcnt lgkmcnt(0)
	v_cvt_pk_bf16_f32 v5, v20, v24
	v_lshl_add_u64 v[6:7], v[22:23], 0, v[6:7]
	global_store_dwordx4 v[6:7], v[2:5], off sc1
	v_add_u32_e32 v6, s24, v122
	v_ashrrev_i32_e32 v7, 31, v6
	v_cvt_pk_bf16_f32 v2, v11, v9
	v_cvt_pk_bf16_f32 v3, v13, v15
	v_cvt_pk_bf16_f32 v4, v17, v19
	v_cvt_pk_bf16_f32 v5, v21, v25
	v_lshlrev_b64 v[6:7], 11, v[6:7]
	ds_read2_b32 v[8:9], v119 offset0:32 offset1:40
	ds_read2_b32 v[10:11], v119 offset0:97 offset1:105
	ds_read2_b32 v[12:13], v119 offset0:162 offset1:170
	ds_read2_b32 v[14:15], v119 offset0:227 offset1:235
	ds_read2_b32 v[16:17], v26 offset0:36 offset1:44
	ds_read2_b32 v[18:19], v26 offset0:101 offset1:109
	ds_read2_b32 v[20:21], v26 offset0:166 offset1:174
	ds_read2_b32 v[24:25], v26 offset0:231 offset1:239
	v_lshl_add_u64 v[6:7], v[22:23], 0, v[6:7]
	global_store_dwordx4 v[6:7], v[2:5], off sc1
	v_add_u32_e32 v6, s24, v123
	v_ashrrev_i32_e32 v7, 31, v6
	v_lshlrev_b64 v[6:7], 11, v[6:7]
	s_waitcnt lgkmcnt(6)
	v_cvt_pk_bf16_f32 v2, v8, v10
	s_waitcnt lgkmcnt(4)
	v_cvt_pk_bf16_f32 v3, v12, v14
	s_waitcnt lgkmcnt(2)
	v_cvt_pk_bf16_f32 v4, v16, v18
	s_waitcnt lgkmcnt(0)
	v_cvt_pk_bf16_f32 v5, v20, v24
	v_lshl_add_u64 v[6:7], v[22:23], 0, v[6:7]
	global_store_dwordx4 v[6:7], v[2:5], off sc1
	v_add_u32_e32 v6, s24, v124
	v_ashrrev_i32_e32 v7, 31, v6
	v_cvt_pk_bf16_f32 v2, v9, v11
	v_cvt_pk_bf16_f32 v3, v13, v15
	v_cvt_pk_bf16_f32 v4, v17, v19
	v_cvt_pk_bf16_f32 v5, v21, v25
	v_lshlrev_b64 v[6:7], 11, v[6:7]
	ds_read2_b32 v[8:9], v119 offset0:48 offset1:56
	ds_read2_b32 v[10:11], v119 offset0:113 offset1:121
	ds_read2_b32 v[12:13], v119 offset0:178 offset1:186
	ds_read2_b32 v[14:15], v119 offset0:243 offset1:251
	ds_read2_b32 v[16:17], v26 offset0:52 offset1:60
	ds_read2_b32 v[18:19], v26 offset0:117 offset1:125
	ds_read2_b32 v[20:21], v26 offset0:182 offset1:190
	ds_read2_b32 v[24:25], v26 offset0:247 offset1:255
	v_lshl_add_u64 v[6:7], v[22:23], 0, v[6:7]
	global_store_dwordx4 v[6:7], v[2:5], off sc1
	v_add_u32_e32 v6, s24, v125
	v_ashrrev_i32_e32 v7, 31, v6
	v_lshlrev_b64 v[6:7], 11, v[6:7]
	s_waitcnt lgkmcnt(6)
	v_cvt_pk_bf16_f32 v2, v8, v10
	s_waitcnt lgkmcnt(4)
	v_cvt_pk_bf16_f32 v3, v12, v14
	s_waitcnt lgkmcnt(2)
	v_cvt_pk_bf16_f32 v4, v16, v18
	s_waitcnt lgkmcnt(0)
	v_cvt_pk_bf16_f32 v5, v20, v24
	v_lshl_add_u64 v[6:7], v[22:23], 0, v[6:7]
	global_store_dwordx4 v[6:7], v[2:5], off sc1
	v_add_u32_e32 v6, s24, v126
	v_ashrrev_i32_e32 v7, 31, v6
	v_lshlrev_b64 v[6:7], 11, v[6:7]
	v_cvt_pk_bf16_f32 v2, v9, v11
	v_cvt_pk_bf16_f32 v3, v13, v15
	v_cvt_pk_bf16_f32 v4, v17, v19
	v_cvt_pk_bf16_f32 v5, v21, v25
	v_lshl_add_u64 v[6:7], v[22:23], 0, v[6:7]
	global_store_dwordx4 v[6:7], v[2:5], off sc1
	s_waitcnt lgkmcnt(0)

; #define GAS __attribute__((address_space(1)))
; #define LAS __attribute__((address_space(3)))
; template <int GU>
; __device__ __forceinline__ void p0_transpose_item(const float* W, int N, const float* kscale, bf16* WT, int ldt, int koff, LAS float* scr, int item, int lane) {
;     const int nblk = N / 64, kb = item / nblk, nb = item % nblk, k0 = 64 * kb, n0 = 64 * nb;
;     const int q = lane >> 4, cc = lane & 15;
;     f32x4 v[16];
; #pragma unroll
;     for (int i = 0; i < 16; ++i) v[i] = *(const GAS f32x4*)(W + (size_t)(k0 + 4 * i + q) * N + n0 + 4 * cc);
;     const int c = lane & 7;
;     f32x4 s0 = (f32x4){1.f, 1.f, 1.f, 1.f}, s1 = s0;
;     if (kscale) { s0 = *(const GAS f32x4*)(kscale + k0 + 8 * c); s1 = *(const GAS f32x4*)(kscale + k0 + 8 * c + 4); }
.LBB0_199:
	s_andn2_b64 vcc, exec, s[36:37]
	s_cbranch_vccnz .LBB0_220
	s_add_i32 s24, s23, 0xfc00
	s_and_b32 s25, s24, 0xffff
	s_mulk_i32 s25, 0x4ec5
	s_lshr_b32 s26, s25, 20
	s_mul_i32 s26, s26, 52
	s_sub_i32 s24, s24, s26
	s_lshr_b32 s25, s25, 14
	s_lshl_b32 s26, s24, 8
	s_and_b32 s25, s25, 0xffc0
	s_and_b32 s84, s26, 0x3ff00
	v_add_u32_e32 v8, s25, v102
	v_lshl_add_u64 v[2:3], v[98:99], 0, s[84:85]
	s_movk_i32 s6, 0x3400
	v_mad_i64_i32 v[4:5], s[26:27], v8, s6, v[2:3]
	v_add_u32_e32 v6, 4, v8
	v_mad_i64_i32 v[6:7], s[26:27], v6, s6, v[2:3]
	global_load_dwordx4 v[72:75], v[4:5], off nt
	global_load_dwordx4 v[54:57], v[6:7], off nt
	v_add_u32_e32 v4, 8, v8
	v_mad_i64_i32 v[4:5], s[26:27], v4, s6, v[2:3]
	v_add_u32_e32 v6, 12, v8
	v_mad_i64_i32 v[6:7], s[26:27], v6, s6, v[2:3]
	global_load_dwordx4 v[68:71], v[4:5], off nt
	global_load_dwordx4 v[46:49], v[6:7], off nt
	v_add_u32_e32 v4, 16, v8
	v_mad_i64_i32 v[4:5], s[26:27], v4, s6, v[2:3]
	v_add_u32_e32 v6, 20, v8
	v_mad_i64_i32 v[6:7], s[26:27], v6, s6, v[2:3]
	global_load_dwordx4 v[62:65], v[4:5], off nt
	global_load_dwordx4 v[38:41], v[6:7], off nt
	v_add_u32_e32 v4, 24, v8
	v_mad_i64_i32 v[4:5], s[26:27], v4, s6, v[2:3]
	v_add_u32_e32 v6, 28, v8
	v_mad_i64_i32 v[6:7], s[26:27], v6, s6, v[2:3]
	global_load_dwordx4 v[58:61], v[4:5], off nt
	global_load_dwordx4 v[26:29], v[6:7], off nt
	v_add_u32_e32 v4, 32, v8
	v_mad_i64_i32 v[4:5], s[26:27], v4, s6, v[2:3]
	v_add_u32_e32 v6, 36, v8
	v_mad_i64_i32 v[6:7], s[26:27], v6, s6, v[2:3]
	global_load_dwordx4 v[50:53], v[4:5], off nt
	global_load_dwordx4 v[22:25], v[6:7], off nt
	v_add_u32_e32 v4, 40, v8
	v_mad_i64_i32 v[4:5], s[26:27], v4, s6, v[2:3]
	v_add_u32_e32 v6, 44, v8
	v_mad_i64_i32 v[6:7], s[26:27], v6, s6, v[2:3]
	global_load_dwordx4 v[42:45], v[4:5], off nt
	global_load_dwordx4 v[18:21], v[6:7], off nt
	v_add_u32_e32 v4, 48, v8
	v_mad_i64_i32 v[4:5], s[26:27], v4, s6, v[2:3]
	v_add_u32_e32 v6, 52, v8
	v_mad_i64_i32 v[6:7], s[26:27], v6, s6, v[2:3]
	global_load_dwordx4 v[30:33], v[4:5], off nt
	global_load_dwordx4 v[10:13], v[6:7], off nt
	v_add_u32_e32 v4, 56, v8
	v_mad_i64_i32 v[4:5], s[26:27], v4, s6, v[2:3]
	v_add_u32_e32 v6, 60, v8
	v_mad_i64_i32 v[2:3], s[26:27], v6, s6, v[2:3]
	global_load_dwordx4 v[34:37], v[4:5], off nt
	global_load_dwordx4 v[14:17], v[2:3], off nt
	v_readlane_b32 s6, v242, 43
	v_readlane_b32 s7, v242, 44
	s_andn2_b64 vcc, exec, s[6:7]
	s_lshl_b32 s24, s24, 6
	s_cbranch_vccnz .LBB0_202
	s_lshl_b32 s84, s25, 2
	v_lshl_add_u64 v[6:7], v[100:101], 0, s[84:85]
	global_load_dwordx4 v[2:5], v[6:7], off offset:16 nt
	s_nop 0
	global_load_dwordx4 v[6:9], v[6:7], off nt
	s_branch .LBB0_203

; #define GAS __attribute__((address_space(1)))
; #define LAS __attribute__((address_space(3)))
; template <int GU>
; __device__ __forceinline__ void p0_transpose_item(const float* W, int N, const float* kscale, bf16* WT, int ldt, int koff, LAS float* scr, int item, int lane) {
;     const int nblk = N / 64, kb = item / nblk, nb = item % nblk, k0 = 64 * kb, n0 = 64 * nb;
;     const int q = lane >> 4, cc = lane & 15;
;     f32x4 v[16];
; #pragma unroll
;     for (int i = 0; i < 16; ++i) v[i] = *(const GAS f32x4*)(W + (size_t)(k0 + 4 * i + q) * N + n0 + 4 * cc);
;     const int c = lane & 7;
;     f32x4 s0 = (f32x4){1.f, 1.f, 1.f, 1.f}, s1 = s0;
;     if (kscale) { s0 = *(const GAS f32x4*)(kscale + k0 + 8 * c); s1 = *(const GAS f32x4*)(kscale + k0 + 8 * c + 4); }
.LBB0_796:
	s_add_i32 s24, s23, 0xfc00
	s_and_b32 s25, s24, 0xffff
	s_mulk_i32 s25, 0x4ec5
	s_lshr_b32 s26, s25, 20
	s_mul_i32 s26, s26, 52
	s_sub_i32 s28, s24, s26
	s_lshr_b32 s24, s25, 14
	s_lshl_b32 s25, s28, 8
	s_and_b32 s24, s24, 0xffc0
	s_and_b32 s84, s25, 0x3ff00
	v_add_u32_e32 v8, s24, v82
	v_lshl_add_u64 v[2:3], v[78:79], 0, s[84:85]
	s_movk_i32 s6, 0x3400
	v_mad_i64_i32 v[4:5], s[26:27], v8, s6, v[2:3]
	v_add_u32_e32 v6, 4, v8
	v_mad_i64_i32 v[6:7], s[26:27], v6, s6, v[2:3]
	global_load_dwordx4 v[72:75], v[4:5], off nt
	global_load_dwordx4 v[54:57], v[6:7], off nt
	v_add_u32_e32 v4, 8, v8
	v_mad_i64_i32 v[4:5], s[26:27], v4, s6, v[2:3]
	v_add_u32_e32 v6, 12, v8
	v_mad_i64_i32 v[6:7], s[26:27], v6, s6, v[2:3]
	global_load_dwordx4 v[68:71], v[4:5], off nt
	global_load_dwordx4 v[46:49], v[6:7], off nt
	v_add_u32_e32 v4, 16, v8
	v_mad_i64_i32 v[4:5], s[26:27], v4, s6, v[2:3]
	v_add_u32_e32 v6, 20, v8
	v_mad_i64_i32 v[6:7], s[26:27], v6, s6, v[2:3]
	global_load_dwordx4 v[62:65], v[4:5], off nt
	global_load_dwordx4 v[38:41], v[6:7], off nt
	v_add_u32_e32 v4, 24, v8
	v_mad_i64_i32 v[4:5], s[26:27], v4, s6, v[2:3]
	v_add_u32_e32 v6, 28, v8
	v_mad_i64_i32 v[6:7], s[26:27], v6, s6, v[2:3]
	global_load_dwordx4 v[58:61], v[4:5], off nt
	global_load_dwordx4 v[26:29], v[6:7], off nt
	v_add_u32_e32 v4, 32, v8
	v_mad_i64_i32 v[4:5], s[26:27], v4, s6, v[2:3]
	v_add_u32_e32 v6, 36, v8
	v_mad_i64_i32 v[6:7], s[26:27], v6, s6, v[2:3]
	global_load_dwordx4 v[50:53], v[4:5], off nt
	global_load_dwordx4 v[22:25], v[6:7], off nt
	v_add_u32_e32 v4, 40, v8
	v_mad_i64_i32 v[4:5], s[26:27], v4, s6, v[2:3]
	v_add_u32_e32 v6, 44, v8
	v_mad_i64_i32 v[6:7], s[26:27], v6, s6, v[2:3]
	global_load_dwordx4 v[42:45], v[4:5], off nt
	global_load_dwordx4 v[18:21], v[6:7], off nt
	v_add_u32_e32 v4, 48, v8
	v_mad_i64_i32 v[4:5], s[26:27], v4, s6, v[2:3]
	v_add_u32_e32 v6, 52, v8
	v_mad_i64_i32 v[6:7], s[26:27], v6, s6, v[2:3]
	global_load_dwordx4 v[30:33], v[4:5], off nt
	global_load_dwordx4 v[10:13], v[6:7], off nt
	v_add_u32_e32 v4, 56, v8
	v_mad_i64_i32 v[4:5], s[26:27], v4, s6, v[2:3]
	v_add_u32_e32 v6, 60, v8
	v_mad_i64_i32 v[2:3], s[26:27], v6, s6, v[2:3]
	global_load_dwordx4 v[34:37], v[4:5], off nt
	global_load_dwordx4 v[14:17], v[2:3], off nt
	v_readlane_b32 s6, v242, 43
	v_readlane_b32 s7, v242, 44
	s_andn2_b64 vcc, exec, s[6:7]
	s_lshl_b32 s25, s28, 6
	s_cbranch_vccnz .LBB0_798
	s_lshl_b32 s84, s24, 2
	v_lshl_add_u64 v[6:7], v[80:81], 0, s[84:85]
	global_load_dwordx4 v[2:5], v[6:7], off offset:16 nt
	s_nop 0
	global_load_dwordx4 v[6:9], v[6:7], off nt
	s_branch .LBB0_799

; __device__ __forceinline__ void p0_pooleff_item(const float* wg, const float* scale, const float* wpb, bf16* WT, int item, int lane) {
;     ...
; #pragma unroll 1
;     for (int j0 = 0; j0 < 128; j0 += 16) {
;         float b[16];
; #pragma unroll
;         for (int u = 0; u < 16; ++u) b[u] = bp[(size_t)(j0 + u) * 1024];
; #pragma unroll
;         for (int u = 0; u < 16; ++u) { const float bb = b[u] * sp[j0 + u];
;             a0 += wgp[0 * 128 + j0 + u] * bb; a1 += wgp[1 * 128 + j0 + u] * bb; a2 += wgp[2 * 128 + j0 + u] * bb; a3 += wgp[3 * 128 + j0 + u] * bb;
;             a4 += wgp[4 * 128 + j0 + u] * bb; a5 += wgp[5 * 128 + j0 + u] * bb; a6 += wgp[6 * 128 + j0 + u] * bb; a7 += wgp[7 * 128 + j0 + u] * bb; }
.LBB0_817:
	v_add_co_u32_e32 v12, vcc, s83, v2
	global_load_dword v28, v[2:3], off
	s_nop 0
	v_addc_co_u32_e32 v13, vcc, 0, v3, vcc
	global_load_dword v29, v[12:13], off offset:-4096
	global_load_dword v30, v[12:13], off
	v_add_co_u32_e32 v12, vcc, s81, v2
	s_add_u32 s28, s23, s44
	s_nop 0
	v_addc_co_u32_e32 v13, vcc, 0, v3, vcc
	global_load_dword v31, v[12:13], off offset:-4096
	global_load_dword v32, v[12:13], off
	v_add_co_u32_e32 v12, vcc, s33, v2
	s_addc_u32 s29, s24, s45
	s_nop 0
	v_addc_co_u32_e32 v13, vcc, 0, v3, vcc
	global_load_dword v65, v[12:13], off offset:-4096
	global_load_dword v139, v[12:13], off
	v_add_co_u32_e32 v12, vcc, s79, v2
	s_nop 1
	v_addc_co_u32_e32 v13, vcc, 0, v3, vcc
	global_load_dword v141, v[12:13], off offset:-4096
	global_load_dword v143, v[12:13], off
	v_add_co_u32_e32 v12, vcc, s20, v2
	s_nop 1
	v_addc_co_u32_e32 v13, vcc, 0, v3, vcc
	global_load_dword v150, v[12:13], off offset:-4096
	global_load_dword v151, v[12:13], off
	v_add_co_u32_e32 v12, vcc, s0, v2
	s_nop 1
	v_addc_co_u32_e32 v13, vcc, 0, v3, vcc
	global_load_dword v152, v[12:13], off offset:-4096
	global_load_dword v153, v[12:13], off
	v_add_co_u32_e32 v12, vcc, s1, v2
	s_nop 1
	v_addc_co_u32_e32 v13, vcc, 0, v3, vcc
	global_load_dword v154, v[12:13], off offset:-4096
	global_load_dword v155, v[12:13], off
	v_add_co_u32_e32 v12, vcc, s21, v2
	s_nop 1
	v_addc_co_u32_e32 v13, vcc, 0, v3, vcc
	global_load_dword v156, v[12:13], off
	s_nop 0
	global_load_dwordx4 v[12:15], v66, s[28:29] offset:2096 nt
	global_load_dwordx4 v[16:19], v66, s[28:29] offset:2080 nt
	global_load_dwordx4 v[20:23], v66, s[28:29] offset:2064 nt
	global_load_dwordx4 v[24:27], v66, s[28:29] offset:2048 nt
	s_add_u32 s28, s25, s44
	s_addc_u32 s29, s26, s45
	s_add_u32 s30, s28, 0x40000
	s_addc_u32 s31, s29, 0
	s_add_u32 s34, s28, 0x40200
	s_addc_u32 s35, s29, 0
	s_add_u32 s36, s28, 0x40400
	s_addc_u32 s37, s29, 0
	s_add_u32 s48, s28, 0x40600
	s_addc_u32 s49, s29, 0
	s_add_u32 s50, s28, 0x40800
	s_addc_u32 s51, s29, 0
	s_add_u32 s56, s28, 0x40a00
	s_addc_u32 s57, s29, 0
	s_add_u32 s58, s28, 0x40c00
	s_addc_u32 s59, s29, 0
	s_add_u32 s60, s28, 0x40e00
	s_addc_u32 s61, s29, 0
	s_add_i32 s27, s27, 16
	s_add_u32 s44, s44, 64
	s_addc_u32 s45, s45, 0
	v_lshl_add_u64 v[2:3], v[2:3], 0, s[54:55]
	s_cmpk_lt_u32 s27, 0x70
	s_waitcnt vmcnt(0)
	v_mul_f32_e32 v12, v153, v12
	v_mul_f32_e32 v16, v143, v16
	v_mul_f32_e32 v20, v32, v20
	v_mul_f32_e32 v64, v28, v24
	v_mul_f32_e32 v138, v29, v25
	v_mul_f32_e32 v140, v30, v26
	v_mul_f32_e32 v142, v31, v27
	global_load_dwordx4 v[24:27], v66, s[30:31] offset:16 nt
	global_load_dwordx4 v[28:31], v66, s[30:31] offset:48 nt
	global_load_dwordx4 v[32:35], v66, s[30:31] offset:32 nt
	global_load_dwordx4 v[36:39], v197, s[28:29] nt
	global_load_dwordx4 v[40:43], v66, s[34:35] offset:16 nt
	global_load_dwordx4 v[44:47], v66, s[34:35] offset:48 nt
	global_load_dwordx4 v[48:51], v66, s[34:35] offset:32 nt
	global_load_dwordx4 v[52:55], v197, s[28:29] offset:512 nt
	v_mul_f32_e32 v22, v139, v22
	v_mul_f32_e32 v18, v151, v18
	v_mul_f32_e32 v14, v155, v14
	s_waitcnt vmcnt(4)
	v_mov_b32_e32 v56, v36
	v_mov_b32_e32 v36, v38
	s_waitcnt vmcnt(0)
	v_mov_b32_e32 v57, v52
	v_pk_fma_f32 v[6:7], v[56:57], v[64:65], v[6:7] op_sel_hi:[1,0,1]
	v_mov_b32_e32 v52, v37
	v_pk_fma_f32 v[6:7], v[52:53], v[138:139], v[6:7] op_sel_hi:[1,0,1]
	v_mov_b32_e32 v37, v54
	v_pk_fma_f32 v[6:7], v[36:37], v[140:141], v[6:7] op_sel_hi:[1,0,1]
	v_mov_b32_e32 v54, v39
	v_pk_fma_f32 v[6:7], v[54:55], v[142:143], v[6:7] op_sel_hi:[1,0,1]
	v_mov_b32_e32 v36, v24
	v_mov_b32_e32 v37, v40
	v_pk_fma_f32 v[144:145], v[36:37], v[20:21], v[6:7] op_sel_hi:[1,0,1]
	global_load_dwordx4 v[36:39], v66, s[36:37] offset:16 nt
	global_load_dwordx4 v[52:55], v66, s[36:37] offset:48 nt
	global_load_dwordx4 v[56:59], v66, s[36:37] offset:32 nt
	global_load_dwordx4 v[60:63], v197, s[28:29] offset:1024 nt
	global_load_dwordx4 v[68:71], v66, s[48:49] offset:16 nt
	global_load_dwordx4 v[72:75], v66, s[48:49] offset:48 nt
	global_load_dwordx4 v[86:89], v66, s[48:49] offset:32 nt
	global_load_dwordx4 v[90:93], v197, s[28:29] offset:1536 nt
	v_mov_b32_e32 v40, v25
	v_mul_f32_e32 v24, v141, v23
	s_waitcnt vmcnt(4)
	v_mov_b32_e32 v6, v60
	s_waitcnt vmcnt(0)
	v_mov_b32_e32 v7, v90
	v_pk_fma_f32 v[6:7], v[64:65], v[6:7], v[8:9] op_sel_hi:[0,1,1]
	v_mov_b32_e32 v90, v61
	v_pk_fma_f32 v[6:7], v[138:139], v[90:91], v[6:7] op_sel_hi:[0,1,1]
	v_mov_b32_e32 v8, v62
	v_mov_b32_e32 v9, v92
	v_pk_fma_f32 v[6:7], v[140:141], v[8:9], v[6:7] op_sel_hi:[0,1,1]
	v_mov_b32_e32 v92, v63
	v_pk_fma_f32 v[6:7], v[142:143], v[92:93], v[6:7] op_sel_hi:[0,1,1]
	v_mov_b32_e32 v8, v36
	v_mov_b32_e32 v9, v68
	v_pk_fma_f32 v[146:147], v[20:21], v[8:9], v[6:7] op_sel_hi:[0,1,1]
	global_load_dwordx4 v[60:63], v66, s[50:51] offset:16 nt
	global_load_dwordx4 v[90:93], v66, s[50:51] offset:48 nt
	global_load_dwordx4 v[94:97], v66, s[50:51] offset:32 nt
	global_load_dwordx4 v[6:9], v197, s[28:29] offset:2048 nt
	global_load_dwordx4 v[98:101], v66, s[56:57] offset:16 nt
	global_load_dwordx4 v[102:105], v66, s[56:57] offset:48 nt
	global_load_dwordx4 v[106:109], v66, s[56:57] offset:32 nt
	global_load_dwordx4 v[110:113], v197, s[28:29] offset:2560 nt
	v_mul_f32_e32 v36, v150, v17
	v_mov_b32_e32 v68, v37
	s_waitcnt vmcnt(4)
	v_mov_b32_e32 v114, v6
	s_waitcnt vmcnt(0)
; __device__ __forceinline__ void p0_pooleff_item(const float* wg, const float* scale, const float* wpb, bf16* WT, int item, int lane) {
;     ...
;     for (int j0 = 0; j0 < 128; j0 += 16) {
;         float b[16];
; #pragma unroll
;         for (int u = 0; u < 16; ++u) b[u] = bp[(size_t)(j0 + u) * 1024];
; #pragma unroll
;         for (int u = 0; u < 16; ++u) { const float bb = b[u] * sp[j0 + u];
;             a0 += wgp[0 * 128 + j0 + u] * bb; a1 += wgp[1 * 128 + j0 + u] * bb; a2 += wgp[2 * 128 + j0 + u] * bb; a3 += wgp[3 * 128 + j0 + u] * bb;
;             a4 += wgp[4 * 128 + j0 + u] * bb; a5 += wgp[5 * 128 + j0 + u] * bb; a6 += wgp[6 * 128 + j0 + u] * bb; a7 += wgp[7 * 128 + j0 + u] * bb; }
;     }
	v_mov_b32_e32 v115, v110
	v_pk_fma_f32 v[10:11], v[64:65], v[114:115], v[10:11] op_sel_hi:[0,1,1]
	v_mov_b32_e32 v110, v7
	v_pk_fma_f32 v[6:7], v[138:139], v[110:111], v[10:11] op_sel_hi:[0,1,1]
	v_mov_b32_e32 v10, v8
	v_mov_b32_e32 v11, v112
	v_pk_fma_f32 v[6:7], v[140:141], v[10:11], v[6:7] op_sel_hi:[0,1,1]
	v_mov_b32_e32 v112, v9
	v_pk_fma_f32 v[6:7], v[142:143], v[112:113], v[6:7] op_sel_hi:[0,1,1]
	v_mov_b32_e32 v8, v60
	v_mov_b32_e32 v9, v98
	v_pk_fma_f32 v[10:11], v[20:21], v[8:9], v[6:7] op_sel_hi:[0,1,1]
	global_load_dwordx4 v[110:113], v66, s[58:59] offset:16 nt
	global_load_dwordx4 v[114:117], v66, s[58:59] offset:48 nt
	global_load_dwordx4 v[118:121], v66, s[58:59] offset:32 nt
	global_load_dwordx4 v[6:9], v197, s[28:29] offset:3072 nt
	global_load_dwordx4 v[122:125], v66, s[60:61] offset:16 nt
	global_load_dwordx4 v[126:129], v66, s[60:61] offset:48 nt
	global_load_dwordx4 v[130:133], v66, s[60:61] offset:32 nt
	global_load_dwordx4 v[134:137], v197, s[28:29] offset:3584 nt
	v_mul_f32_e32 v60, v152, v19
	v_mov_b32_e32 v98, v61
	s_waitcnt vmcnt(4)
	v_mov_b32_e32 v148, v6
	v_mov_b32_e32 v6, v8
	v_mov_b32_e32 v8, v26
	v_mov_b32_e32 v26, v38
	s_waitcnt vmcnt(0)
	v_mov_b32_e32 v149, v134
	v_pk_fma_f32 v[4:5], v[64:65], v[148:149], v[4:5] op_sel_hi:[0,1,1]
	v_mov_b32_e32 v134, v7
	v_pk_fma_f32 v[4:5], v[138:139], v[134:135], v[4:5] op_sel_hi:[0,1,1]
	v_mov_b32_e32 v7, v136
	v_pk_fma_f32 v[4:5], v[140:141], v[6:7], v[4:5] op_sel_hi:[0,1,1]
	v_mov_b32_e32 v136, v9
	v_pk_fma_f32 v[4:5], v[142:143], v[136:137], v[4:5] op_sel_hi:[0,1,1]
	v_mov_b32_e32 v6, v110
	v_mov_b32_e32 v7, v122
	v_pk_fma_f32 v[4:5], v[20:21], v[6:7], v[4:5] op_sel_hi:[0,1,1]
	v_mul_f32_e32 v20, v65, v21
	v_pk_fma_f32 v[6:7], v[40:41], v[20:21], v[144:145] op_sel_hi:[1,0,1]
	v_mov_b32_e32 v9, v42
	v_pk_fma_f32 v[6:7], v[8:9], v[22:23], v[6:7] op_sel_hi:[1,0,1]
	v_mov_b32_e32 v42, v27
	v_pk_fma_f32 v[6:7], v[42:43], v[24:25], v[6:7] op_sel_hi:[1,0,1]
	v_mov_b32_e32 v8, v32
	v_mov_b32_e32 v9, v48
	v_pk_fma_f32 v[6:7], v[8:9], v[16:17], v[6:7] op_sel_hi:[1,0,1]
	v_mov_b32_e32 v48, v33
	v_pk_fma_f32 v[6:7], v[48:49], v[36:37], v[6:7] op_sel_hi:[1,0,1]
	v_mov_b32_e32 v8, v34
	v_mov_b32_e32 v9, v50
	v_pk_fma_f32 v[6:7], v[8:9], v[18:19], v[6:7] op_sel_hi:[1,0,1]
	v_mov_b32_e32 v50, v35
	v_pk_fma_f32 v[6:7], v[50:51], v[60:61], v[6:7] op_sel_hi:[1,0,1]
	v_mov_b32_e32 v8, v28
	v_mov_b32_e32 v9, v44
	v_mul_f32_e32 v64, v154, v13
	v_pk_fma_f32 v[6:7], v[8:9], v[12:13], v[6:7] op_sel_hi:[1,0,1]
	v_mov_b32_e32 v44, v29
	v_pk_fma_f32 v[6:7], v[44:45], v[64:65], v[6:7] op_sel_hi:[1,0,1]
	v_mov_b32_e32 v8, v30
	v_mov_b32_e32 v9, v46
	v_pk_fma_f32 v[6:7], v[8:9], v[14:15], v[6:7] op_sel_hi:[1,0,1]
	v_pk_fma_f32 v[8:9], v[20:21], v[68:69], v[146:147] op_sel_hi:[0,1,1]
	v_mov_b32_e32 v27, v70
	v_pk_fma_f32 v[8:9], v[22:23], v[26:27], v[8:9] op_sel_hi:[0,1,1]
	v_mov_b32_e32 v70, v39
	v_pk_fma_f32 v[8:9], v[24:25], v[70:71], v[8:9] op_sel_hi:[0,1,1]
	v_mov_b32_e32 v26, v56
	v_mov_b32_e32 v27, v86
	v_pk_fma_f32 v[8:9], v[16:17], v[26:27], v[8:9] op_sel_hi:[0,1,1]
	v_mov_b32_e32 v86, v57
	v_pk_fma_f32 v[8:9], v[36:37], v[86:87], v[8:9] op_sel_hi:[0,1,1]
	v_mov_b32_e32 v26, v58
	v_mov_b32_e32 v27, v88
	v_pk_fma_f32 v[8:9], v[18:19], v[26:27], v[8:9] op_sel_hi:[0,1,1]
	v_mov_b32_e32 v88, v59
	v_pk_fma_f32 v[8:9], v[60:61], v[88:89], v[8:9] op_sel_hi:[0,1,1]
	v_mov_b32_e32 v26, v52
	v_mov_b32_e32 v27, v72
	v_pk_fma_f32 v[8:9], v[12:13], v[26:27], v[8:9] op_sel_hi:[0,1,1]
	v_mov_b32_e32 v72, v53
	v_mov_b32_e32 v122, v111
	v_pk_fma_f32 v[8:9], v[64:65], v[72:73], v[8:9] op_sel_hi:[0,1,1]
	v_mov_b32_e32 v26, v54
	v_mov_b32_e32 v27, v74
	v_pk_fma_f32 v[8:9], v[14:15], v[26:27], v[8:9] op_sel_hi:[0,1,1]
	v_pk_fma_f32 v[10:11], v[20:21], v[98:99], v[10:11] op_sel_hi:[0,1,1]
	v_mov_b32_e32 v26, v62
	v_mov_b32_e32 v27, v100
	v_pk_fma_f32 v[4:5], v[20:21], v[122:123], v[4:5] op_sel_hi:[0,1,1]
	v_mov_b32_e32 v20, v112
	v_mov_b32_e32 v21, v124
	v_pk_fma_f32 v[10:11], v[22:23], v[26:27], v[10:11] op_sel_hi:[0,1,1]
	v_mov_b32_e32 v100, v63
	v_pk_fma_f32 v[4:5], v[22:23], v[20:21], v[4:5] op_sel_hi:[0,1,1]
	v_mov_b32_e32 v124, v113
	v_pk_fma_f32 v[10:11], v[24:25], v[100:101], v[10:11] op_sel_hi:[0,1,1]
	v_mov_b32_e32 v26, v94
	v_mov_b32_e32 v27, v106
	v_pk_fma_f32 v[4:5], v[24:25], v[124:125], v[4:5] op_sel_hi:[0,1,1]
	v_mov_b32_e32 v20, v118
	v_mov_b32_e32 v21, v130
	v_pk_fma_f32 v[10:11], v[16:17], v[26:27], v[10:11] op_sel_hi:[0,1,1]
	v_mov_b32_e32 v106, v95
	v_pk_fma_f32 v[4:5], v[16:17], v[20:21], v[4:5] op_sel_hi:[0,1,1]
	v_mov_b32_e32 v130, v119
	v_pk_fma_f32 v[10:11], v[36:37], v[106:107], v[10:11] op_sel_hi:[0,1,1]
	v_mov_b32_e32 v26, v96
	v_mov_b32_e32 v27, v108
	v_pk_fma_f32 v[4:5], v[36:37], v[130:131], v[4:5] op_sel_hi:[0,1,1]
	v_mov_b32_e32 v16, v120
	v_mov_b32_e32 v17, v132
	v_pk_fma_f32 v[10:11], v[18:19], v[26:27], v[10:11] op_sel_hi:[0,1,1]
	v_mov_b32_e32 v108, v97
	v_pk_fma_f32 v[4:5], v[18:19], v[16:17], v[4:5] op_sel_hi:[0,1,1]
	v_mov_b32_e32 v132, v121
	v_pk_fma_f32 v[10:11], v[60:61], v[108:109], v[10:11] op_sel_hi:[0,1,1]
	v_mov_b32_e32 v26, v90
	v_mov_b32_e32 v27, v102
	v_pk_fma_f32 v[4:5], v[60:61], v[132:133], v[4:5] op_sel_hi:[0,1,1]
	v_mov_b32_e32 v16, v114
	v_mov_b32_e32 v17, v126
	v_pk_fma_f32 v[10:11], v[12:13], v[26:27], v[10:11] op_sel_hi:[0,1,1]
	v_mov_b32_e32 v102, v91
	v_pk_fma_f32 v[4:5], v[12:13], v[16:17], v[4:5] op_sel_hi:[0,1,1]
	v_mov_b32_e32 v126, v115
	v_pk_fma_f32 v[10:11], v[64:65], v[102:103], v[10:11] op_sel_hi:[0,1,1]
	v_mov_b32_e32 v26, v92
	v_mov_b32_e32 v27, v104
	v_pk_fma_f32 v[4:5], v[64:65], v[126:127], v[4:5] op_sel_hi:[0,1,1]
	v_mov_b32_e32 v12, v116
	v_mov_b32_e32 v13, v128
	v_mul_f32_e32 v110, v156, v15
	v_mov_b32_e32 v46, v31
	v_mov_b32_e32 v74, v55
	v_pk_fma_f32 v[10:11], v[14:15], v[26:27], v[10:11] op_sel_hi:[0,1,1]
	v_mov_b32_e32 v104, v93
	v_pk_fma_f32 v[4:5], v[14:15], v[12:13], v[4:5] op_sel_hi:[0,1,1]
	v_mov_b32_e32 v128, v117
	v_pk_fma_f32 v[6:7], v[46:47], v[110:111], v[6:7] op_sel_hi:[1,0,1]
	v_pk_fma_f32 v[8:9], v[110:111], v[74:75], v[8:9] op_sel_hi:[0,1,1]
	v_pk_fma_f32 v[10:11], v[110:111], v[104:105], v[10:11] op_sel_hi:[0,1,1]
	v_pk_fma_f32 v[4:5], v[110:111], v[128:129], v[4:5] op_sel_hi:[0,1,1]
	s_cbranch_scc1 .LBB0_817
; #define GAS __attribute__((address_space(1)))
; __device__ __forceinline__ unsigned pk2(float lo, float hi) { f32x2p v = {lo, hi}; bf16x2p b = __builtin_convertvector(v, bf16x2p); return __builtin_bit_cast(unsigned, b); }
; __device__ __forceinline__ void p0_pooleff_item(const float* wg, const float* scale, const float* wpb, bf16* WT, int item, int lane) {
;     ...
;     v4u o; o.x = pk2(a0, a1); o.y = pk2(a2, a3); o.z = pk2(a4, a5); o.w = pk2(a6, a7);
;     *(GAS v4u*)(WT + (size_t)n * 1024 + g * 128 + cblk * 8) = o;
	s_lshl_b32 s23, s47, 6
	s_and_b32 s23, s23, 0x3c0
	v_add_u32_e32 v2, s23, v67
	v_ashrrev_i32_e32 v3, 31, v2
	v_readlane_b32 s4, v241, 19
	v_lshlrev_b64 v[2:3], 11, v[2:3]
	v_readlane_b32 s5, v241, 20
	s_and_b32 s84, s47, 0xf0
	v_cvt_pk_bf16_f32 v6, v6, v7
	v_lshl_add_u64 v[2:3], s[4:5], 0, v[2:3]
	v_lshl_add_u64 v[2:3], s[42:43], 1, v[2:3]
	v_cvt_pk_bf16_f32 v7, v8, v9
	v_cvt_pk_bf16_f32 v8, v10, v11
	v_cvt_pk_bf16_f32 v9, v4, v5
	v_lshl_add_u64 v[2:3], v[2:3], 0, s[84:85]
	v_readlane_b32 s4, v242, 0
	v_readlane_b32 s8, v238, 33
	v_readlane_b32 s10, v238, 35
	v_readlane_b32 s14, v238, 37
	v_readlane_b32 s16, v242, 62
	v_readlane_b32 s18, v240, 0
	v_readlane_b32 s34, v240, 2
	global_store_dwordx4 v[2:3], v[6:9], off sc1
	v_readlane_b32 s2, v242, 4
	v_readlane_b32 s5, v242, 1
	v_readlane_b32 s9, v238, 34
	v_readlane_b32 s11, v238, 36
	v_readlane_b32 s15, v238, 38
	v_readlane_b32 s17, v242, 63
	v_readlane_b32 s19, v240, 1
	v_readlane_b32 s35, v240, 3
	s_branch .LBB0_793
